# mixC + mlstmA regions: 364 packed f32 VOP3P ops beside MFMAs split into scalar halves (bit-identical), on top of the packed-softmax kernel
# baseline (speedup 1.0000x reference)
; DI u16 f2bf(float x) { return (u16)(pack2(x, 0.f) & 0xffffu); }
; DI void conv_unit(const u16* __restrict__ PM, const float* __restrict__ conv_w, const float* __restrict__ conv_b, int b, int sl0, int ch, float scale, float* a8) {
;   { const float4 b0 = *(const float4*)(conv_b + ch), b1 = *(const float4*)(conv_b + ch + 4); a8[0] = b0.x; a8[1] = b0.y; a8[2] = b0.z; a8[3] = b0.w; a8[4] = b1.x; a8[5] = b1.y; a8[6] = b1.z; a8[7] = b1.w; }
; #pragma unroll
;   for (int j = 0; j < 4; ++j) {
;     const int sl = sl0 - 3 + j;
;     if (sl >= 0) {
;       const uint4 raw = *(const uint4*)(PM + ((size_t)b * SEQ + sl) * 1024 + ch);
;       float x8[8]; unpack8(raw, x8);
;       const float4 w0 = *(const float4*)(conv_w + j * 1024 + ch), w1 = *(const float4*)(conv_w + j * 1024 + ch + 4);
;       a8[0] += w0.x * x8[0]; a8[1] += w0.y * x8[1]; a8[2] += w0.z * x8[2]; a8[3] += w0.w * x8[3];
;       a8[4] += w1.x * x8[4]; a8[5] += w1.y * x8[5]; a8[6] += w1.z * x8[6]; a8[7] += w1.w * x8[7];
;     }
;   }
; #pragma unroll
;   for (int e = 0; e < 8; ++e) { const float v = a8[e]; a8[e] = scale * v * __builtin_amdgcn_rcpf(1.f + __expf(-v)); }
; DI void mlstmA_item(const Params& p, char* lds, int item) {
;     ...
;     conv_unit(PM, p.in[5], p.in[6], b, c * 64 + t, 512 + hd * 128 + cgk * 8, 0.08838834764831845f, a8);
;     const float w = win[t];
; #pragma unroll
;     for (int e = 0; e < 8; ++e) KTs[(cgk * 8 + e) * 72 + t] = f2bf(a8[e] * w);
.LBB0_330:
	s_or_b64 exec, exec, s[14:15]
	v_add_u32_e32 v4, 0x200, v18
	s_and_b32 s0, s10, 0xffffff80
	v_lshlrev_b32_e32 v2, 4, v18
	v_ashrrev_i32_e32 v9, 3, v18
	v_ashrrev_i32_e32 v14, 3, v4
	v_and_b32_e32 v16, 0x70, v2
	v_add_u32_e32 v2, s0, v9
	v_add_u32_e32 v4, s0, v14
	v_lshl_add_u64 v[0:1], v[0:1], 1, s[6:7]
	v_ashrrev_i32_e32 v3, 31, v2
	v_ashrrev_i32_e32 v5, 31, v4
	v_lshl_add_u64 v[0:1], v[0:1], 0, v[16:17]
	v_lshlrev_b64 v[2:3], 14, v[2:3]
	v_lshlrev_b64 v[4:5], 14, v[4:5]
	v_lshl_add_u64 v[2:3], v[0:1], 0, v[2:3]
	v_lshl_add_u64 v[4:5], v[0:1], 0, v[4:5]
	v_lshlrev_b32_e32 v8, 3, v18
	v_and_b32_e32 v22, 0x78, v8
	v_add_u32_e32 v8, 0, v16
	v_lshl_or_b32 v15, s27, 7, v22
	v_mad_u64_u32 v[12:13], s[0:1], v9, s26, v[8:9]
	v_lshlrev_b32_e32 v16, 2, v15
	v_mad_u64_u32 v[8:9], s[0:1], v14, s26, v[8:9]
	v_lshlrev_b64 v[10:11], 24, v[10:11]
	v_lshl_add_u64 v[10:11], s[4:5], 0, v[10:11]
	v_mov_b32_e32 v13, v17
	s_mov_b64 s[0:1], 0x1800
	v_ashrrev_i32_e32 v51, 4, v18
	v_mad_u32_u24 v52, v22, s26, 0
	s_mov_b32 s8, 0
	s_waitcnt vmcnt(20)
	ds_write_b128 v12, v[232:235] offset:18432
	ds_write_b128 v8, v[236:239] offset:18432
	s_waitcnt lgkmcnt(0)
	s_barrier
	s_add_i32 s97, s10, s70
	v_add_u32_e32 v240, 0x200, v222
	s_and_b32 s73, s97, 0xffffff80
	v_lshlrev_b32_e32 v241, 4, v222
	v_ashrrev_i32_e32 v242, 3, v222
	v_ashrrev_i32_e32 v244, 3, v240
	v_and_b32_e32 v246, 0x70, v241
	v_mov_b32_e32 v247, 0
	v_add_u32_e32 v242, s73, v242
	v_add_u32_e32 v244, s73, v244
	s_and_b32 s78, s97, 0x7f
	s_lshl_b32 s78, s78, 7
	v_mov_b32_e32 v248, s78
	v_mov_b32_e32 v249, 0
	v_lshl_add_u64 v[248:249], s[6:7], 0, v[248:249]
	v_lshl_add_u64 v[248:249], v[248:249], 0, v[246:247]
	v_ashrrev_i32_e32 v243, 31, v242
	v_ashrrev_i32_e32 v245, 31, v244
	v_lshlrev_b64 v[242:243], 14, v[242:243]
	v_lshlrev_b64 v[244:245], 14, v[244:245]
	v_lshl_add_u64 v[242:243], v[248:249], 0, v[242:243]
	v_lshl_add_u64 v[244:245], v[248:249], 0, v[244:245]
	global_load_dwordx4 v[232:235], v[242:243], off
	global_load_dwordx4 v[236:239], v[244:245], off
	s_waitcnt vmcnt(2)
	v_mov_b32_e32 v197, v51
	v_lshl_add_u32 v196, v197, 2, s96
	ds_read_b32 v196, v196 offset:40960
	v_lshl_add_u32 v198, v197, 1, v52
	v_lshlrev_b32_e32 v188, 16, v114
	v_and_b32_e32 v189, 0xffff0000, v114
	v_lshlrev_b32_e32 v190, 16, v115
	v_and_b32_e32 v191, 0xffff0000, v115
	v_lshlrev_b32_e32 v192, 16, v116
	v_and_b32_e32 v193, 0xffff0000, v116
	v_lshlrev_b32_e32 v194, 16, v117
	v_and_b32_e32 v195, 0xffff0000, v117
	v_fma_f32 v204, v140, v188, v224
	v_fma_f32 v205, v141, v189, v225
	v_fma_f32 v206, v142, v190, v226
	v_fma_f32 v207, v143, v191, v227
	v_fma_f32 v208, v144, v192, v228
	v_fma_f32 v209, v145, v193, v229
	v_fma_f32 v210, v146, v194, v230
	v_fma_f32 v211, v147, v195, v231
	v_lshlrev_b32_e32 v188, 16, v118
	v_and_b32_e32 v189, 0xffff0000, v118
	v_lshlrev_b32_e32 v190, 16, v119
	v_and_b32_e32 v191, 0xffff0000, v119
	v_lshlrev_b32_e32 v192, 16, v120
	v_and_b32_e32 v193, 0xffff0000, v120
	v_lshlrev_b32_e32 v194, 16, v121
	v_and_b32_e32 v195, 0xffff0000, v121
	v_fmac_f32_e32 v204, v148, v188
	v_fmac_f32_e32 v205, v149, v189
	v_fmac_f32_e32 v206, v150, v190
	v_fmac_f32_e32 v207, v151, v191
	v_fmac_f32_e32 v208, v152, v192
	v_fmac_f32_e32 v209, v153, v193
	v_fmac_f32_e32 v210, v154, v194
	v_fmac_f32_e32 v211, v155, v195
	v_lshlrev_b32_e32 v188, 16, v122
	v_and_b32_e32 v189, 0xffff0000, v122
	v_lshlrev_b32_e32 v190, 16, v123
	v_and_b32_e32 v191, 0xffff0000, v123
	v_lshlrev_b32_e32 v192, 16, v124
	v_and_b32_e32 v193, 0xffff0000, v124
	v_lshlrev_b32_e32 v194, 16, v125
	v_and_b32_e32 v195, 0xffff0000, v125
	v_fmac_f32_e32 v204, v156, v188
	v_fmac_f32_e32 v205, v157, v189
	v_fmac_f32_e32 v206, v158, v190
	v_fmac_f32_e32 v207, v159, v191
	v_fmac_f32_e32 v208, v160, v192
	v_fmac_f32_e32 v209, v161, v193
	v_fmac_f32_e32 v210, v162, v194
	v_fmac_f32_e32 v211, v163, v195
	v_lshlrev_b32_e32 v188, 16, v126
	v_and_b32_e32 v189, 0xffff0000, v126
	v_lshlrev_b32_e32 v190, 16, v127
	v_and_b32_e32 v191, 0xffff0000, v127
	v_lshlrev_b32_e32 v192, 16, v128
	v_and_b32_e32 v193, 0xffff0000, v128
	v_lshlrev_b32_e32 v194, 16, v129
	v_and_b32_e32 v195, 0xffff0000, v129
	v_fmac_f32_e32 v204, v164, v188
	v_fmac_f32_e32 v205, v165, v189
	v_fmac_f32_e32 v206, v166, v190
	v_fmac_f32_e32 v207, v167, v191
	v_fmac_f32_e32 v208, v168, v192
	v_fmac_f32_e32 v209, v169, v193
	v_fmac_f32_e32 v210, v170, v194
	v_fmac_f32_e32 v211, v171, v195
	v_mul_f32_e32 v212, 0xbfb8aa3b, v204
	v_mul_f32_e32 v213, 0xbfb8aa3b, v205
	v_mul_f32_e32 v214, 0xbfb8aa3b, v206
	v_mul_f32_e32 v215, 0xbfb8aa3b, v207
	v_mul_f32_e32 v216, 0xbfb8aa3b, v208
	v_mul_f32_e32 v217, 0xbfb8aa3b, v209
	v_mul_f32_e32 v218, 0xbfb8aa3b, v210
	v_mul_f32_e32 v219, 0xbfb8aa3b, v211
	v_mul_f32_e32 v188, 0x3db504f3, v204
	v_mul_f32_e32 v189, 0x3db504f3, v205
	v_mul_f32_e32 v190, 0x3db504f3, v206
	v_mul_f32_e32 v191, 0x3db504f3, v207
	v_mul_f32_e32 v192, 0x3db504f3, v208
	v_mul_f32_e32 v193, 0x3db504f3, v209
	v_mul_f32_e32 v194, 0x3db504f3, v210
	v_mul_f32_e32 v195, 0x3db504f3, v211
	v_exp_f32_e32 v212, v212
	v_exp_f32_e32 v213, v213
	v_exp_f32_e32 v214, v214
	v_exp_f32_e32 v215, v215
	v_exp_f32_e32 v216, v216
	v_exp_f32_e32 v217, v217
	v_exp_f32_e32 v218, v218
	v_exp_f32_e32 v219, v219
	v_add_f32_e32 v212, 1.0, v212
	v_add_f32_e32 v213, 1.0, v213
	v_add_f32_e32 v214, 1.0, v214
	v_add_f32_e32 v215, 1.0, v215
	v_add_f32_e32 v216, 1.0, v216
	v_add_f32_e32 v217, 1.0, v217
	v_add_f32_e32 v218, 1.0, v218
	v_add_f32_e32 v219, 1.0, v219
	v_rcp_f32_e32 v212, v212
	v_rcp_f32_e32 v213, v213
	v_rcp_f32_e32 v214, v214
	v_rcp_f32_e32 v215, v215
	v_rcp_f32_e32 v216, v216
	v_rcp_f32_e32 v217, v217
	v_rcp_f32_e32 v218, v218
	v_rcp_f32_e32 v219, v219
	v_mul_f32_e32 v188, v188, v212
	v_mul_f32_e32 v189, v189, v213
	v_mul_f32_e32 v190, v190, v214
	v_mul_f32_e32 v191, v191, v215
	v_mul_f32_e32 v192, v192, v216
	v_mul_f32_e32 v193, v193, v217
	v_mul_f32_e32 v194, v194, v218
	v_mul_f32_e32 v195, v195, v219
	s_waitcnt lgkmcnt(0)
; DI u16 f2bf(float x) { return (u16)(pack2(x, 0.f) & 0xffffu); }
; DI void conv_unit(const u16* __restrict__ PM, const float* __restrict__ conv_w, const float* __restrict__ conv_b, int b, int sl0, int ch, float scale, float* a8) {
;   { const float4 b0 = *(const float4*)(conv_b + ch), b1 = *(const float4*)(conv_b + ch + 4); a8[0] = b0.x; a8[1] = b0.y; a8[2] = b0.z; a8[3] = b0.w; a8[4] = b1.x; a8[5] = b1.y; a8[6] = b1.z; a8[7] = b1.w; }
; #pragma unroll
;   for (int j = 0; j < 4; ++j) {
;     const int sl = sl0 - 3 + j;
;     if (sl >= 0) {
;       const uint4 raw = *(const uint4*)(PM + ((size_t)b * SEQ + sl) * 1024 + ch);
;       float x8[8]; unpack8(raw, x8);
;       const float4 w0 = *(const float4*)(conv_w + j * 1024 + ch), w1 = *(const float4*)(conv_w + j * 1024 + ch + 4);
;       a8[0] += w0.x * x8[0]; a8[1] += w0.y * x8[1]; a8[2] += w0.z * x8[2]; a8[3] += w0.w * x8[3];
;       a8[4] += w1.x * x8[4]; a8[5] += w1.y * x8[5]; a8[6] += w1.z * x8[6]; a8[7] += w1.w * x8[7];
;     }
;   }
; #pragma unroll
;   for (int e = 0; e < 8; ++e) { const float v = a8[e]; a8[e] = scale * v * __builtin_amdgcn_rcpf(1.f + __expf(-v)); }
; DI void mlstmA_item(const Params& p, char* lds, int item) {
;     ...
;     conv_unit(PM, p.in[5], p.in[6], b, c * 64 + t, 512 + hd * 128 + cgk * 8, 0.08838834764831845f, a8);
;     const float w = win[t];
; #pragma unroll
;     for (int e = 0; e < 8; ++e) KTs[(cgk * 8 + e) * 72 + t] = f2bf(a8[e] * w);
	v_mul_f32_e32 v188, v196, v188
	v_mul_f32_e32 v189, v196, v189
	v_mul_f32_e32 v190, v196, v190
	v_mul_f32_e32 v191, v196, v191
	v_mul_f32_e32 v192, v196, v192
	v_mul_f32_e32 v193, v196, v193
	v_mul_f32_e32 v194, v196, v194
	v_mul_f32_e32 v195, v196, v195
	v_cvt_pk_bf16_f32 v188, v188, s77
	v_cvt_pk_bf16_f32 v189, v189, s77
	v_cvt_pk_bf16_f32 v190, v190, s77
	v_cvt_pk_bf16_f32 v191, v191, s77
	v_cvt_pk_bf16_f32 v192, v192, s77
	v_cvt_pk_bf16_f32 v193, v193, s77
	v_cvt_pk_bf16_f32 v194, v194, s77
	v_cvt_pk_bf16_f32 v195, v195, s77
	ds_write_b16 v198, v188
	ds_write_b16 v198, v189 offset:144
	ds_write_b16 v198, v190 offset:288
	ds_write_b16 v198, v191 offset:432
	ds_write_b16 v198, v192 offset:576
	ds_write_b16 v198, v193 offset:720
	ds_write_b16 v198, v194 offset:864
	ds_write_b16 v198, v195 offset:1008
	v_add_u32_e32 v197, 32, v51
	v_lshl_add_u32 v196, v197, 2, s96
	ds_read_b32 v196, v196 offset:40960
	v_lshl_add_u32 v198, v197, 1, v52
	v_lshlrev_b32_e32 v188, 16, v130
	v_and_b32_e32 v189, 0xffff0000, v130
	v_lshlrev_b32_e32 v190, 16, v131
	v_and_b32_e32 v191, 0xffff0000, v131
	v_lshlrev_b32_e32 v192, 16, v132
	v_and_b32_e32 v193, 0xffff0000, v132
	v_lshlrev_b32_e32 v194, 16, v133
	v_and_b32_e32 v195, 0xffff0000, v133
	v_fma_f32 v204, v140, v188, v224
	v_fma_f32 v205, v141, v189, v225
	v_fma_f32 v206, v142, v190, v226
	v_fma_f32 v207, v143, v191, v227
	v_fma_f32 v208, v144, v192, v228
	v_fma_f32 v209, v145, v193, v229
	v_fma_f32 v210, v146, v194, v230
	v_fma_f32 v211, v147, v195, v231
	v_lshlrev_b32_e32 v188, 16, v134
	v_and_b32_e32 v189, 0xffff0000, v134
	v_lshlrev_b32_e32 v190, 16, v135
	v_and_b32_e32 v191, 0xffff0000, v135
	v_lshlrev_b32_e32 v192, 16, v136
	v_and_b32_e32 v193, 0xffff0000, v136
	v_lshlrev_b32_e32 v194, 16, v137
	v_and_b32_e32 v195, 0xffff0000, v137
	v_fmac_f32_e32 v204, v148, v188
	v_fmac_f32_e32 v205, v149, v189
	v_fmac_f32_e32 v206, v150, v190
	v_fmac_f32_e32 v207, v151, v191
	v_fmac_f32_e32 v208, v152, v192
	v_fmac_f32_e32 v209, v153, v193
	v_fmac_f32_e32 v210, v154, v194
	v_fmac_f32_e32 v211, v155, v195
	v_lshlrev_b32_e32 v188, 16, v172
	v_and_b32_e32 v189, 0xffff0000, v172
	v_lshlrev_b32_e32 v190, 16, v173
	v_and_b32_e32 v191, 0xffff0000, v173
	v_lshlrev_b32_e32 v192, 16, v174
	v_and_b32_e32 v193, 0xffff0000, v174
	v_lshlrev_b32_e32 v194, 16, v175
	v_and_b32_e32 v195, 0xffff0000, v175
	v_fmac_f32_e32 v204, v156, v188
	v_fmac_f32_e32 v205, v157, v189
	v_fmac_f32_e32 v206, v158, v190
	v_fmac_f32_e32 v207, v159, v191
	v_fmac_f32_e32 v208, v160, v192
	v_fmac_f32_e32 v209, v161, v193
	v_fmac_f32_e32 v210, v162, v194
	v_fmac_f32_e32 v211, v163, v195
	v_lshlrev_b32_e32 v188, 16, v176
	v_and_b32_e32 v189, 0xffff0000, v176
	v_lshlrev_b32_e32 v190, 16, v177
	v_and_b32_e32 v191, 0xffff0000, v177
	v_lshlrev_b32_e32 v192, 16, v178
	v_and_b32_e32 v193, 0xffff0000, v178
	v_lshlrev_b32_e32 v194, 16, v179
	v_and_b32_e32 v195, 0xffff0000, v179
	v_fmac_f32_e32 v204, v164, v188
	v_fmac_f32_e32 v205, v165, v189
	v_fmac_f32_e32 v206, v166, v190
	v_fmac_f32_e32 v207, v167, v191
	v_fmac_f32_e32 v208, v168, v192
	v_fmac_f32_e32 v209, v169, v193
	v_fmac_f32_e32 v210, v170, v194
	v_fmac_f32_e32 v211, v171, v195
	v_mul_f32_e32 v212, 0xbfb8aa3b, v204
	v_mul_f32_e32 v213, 0xbfb8aa3b, v205
	v_mul_f32_e32 v214, 0xbfb8aa3b, v206
	v_mul_f32_e32 v215, 0xbfb8aa3b, v207
	v_mul_f32_e32 v216, 0xbfb8aa3b, v208
	v_mul_f32_e32 v217, 0xbfb8aa3b, v209
	v_mul_f32_e32 v218, 0xbfb8aa3b, v210
	v_mul_f32_e32 v219, 0xbfb8aa3b, v211
	v_mul_f32_e32 v188, 0x3db504f3, v204
	v_mul_f32_e32 v189, 0x3db504f3, v205
	v_mul_f32_e32 v190, 0x3db504f3, v206
	v_mul_f32_e32 v191, 0x3db504f3, v207
	v_mul_f32_e32 v192, 0x3db504f3, v208
	v_mul_f32_e32 v193, 0x3db504f3, v209
	v_mul_f32_e32 v194, 0x3db504f3, v210
	v_mul_f32_e32 v195, 0x3db504f3, v211
	v_exp_f32_e32 v212, v212
	v_exp_f32_e32 v213, v213
	v_exp_f32_e32 v214, v214
	v_exp_f32_e32 v215, v215
	v_exp_f32_e32 v216, v216
	v_exp_f32_e32 v217, v217
	v_exp_f32_e32 v218, v218
	v_exp_f32_e32 v219, v219
	v_add_f32_e32 v212, 1.0, v212
	v_add_f32_e32 v213, 1.0, v213
	v_add_f32_e32 v214, 1.0, v214
	v_add_f32_e32 v215, 1.0, v215
	v_add_f32_e32 v216, 1.0, v216
	v_add_f32_e32 v217, 1.0, v217
	v_add_f32_e32 v218, 1.0, v218
	v_add_f32_e32 v219, 1.0, v219
	v_rcp_f32_e32 v212, v212
	v_rcp_f32_e32 v213, v213
	v_rcp_f32_e32 v214, v214
	v_rcp_f32_e32 v215, v215
	v_rcp_f32_e32 v216, v216
	v_rcp_f32_e32 v217, v217
	v_rcp_f32_e32 v218, v218
	v_rcp_f32_e32 v219, v219
	v_mul_f32_e32 v188, v188, v212
	v_mul_f32_e32 v189, v189, v213
	v_mul_f32_e32 v190, v190, v214
	v_mul_f32_e32 v191, v191, v215
	v_mul_f32_e32 v192, v192, v216
	v_mul_f32_e32 v193, v193, v217
	v_mul_f32_e32 v194, v194, v218
	v_mul_f32_e32 v195, v195, v219
	s_waitcnt lgkmcnt(0)
; DI u16 f2bf(float x) { return (u16)(pack2(x, 0.f) & 0xffffu); }
; DI void conv_unit(const u16* __restrict__ PM, const float* __restrict__ conv_w, const float* __restrict__ conv_b, int b, int sl0, int ch, float scale, float* a8) {
;   { const float4 b0 = *(const float4*)(conv_b + ch), b1 = *(const float4*)(conv_b + ch + 4); a8[0] = b0.x; a8[1] = b0.y; a8[2] = b0.z; a8[3] = b0.w; a8[4] = b1.x; a8[5] = b1.y; a8[6] = b1.z; a8[7] = b1.w; }
; #pragma unroll
;   for (int j = 0; j < 4; ++j) {
;     const int sl = sl0 - 3 + j;
;     if (sl >= 0) {
;       const uint4 raw = *(const uint4*)(PM + ((size_t)b * SEQ + sl) * 1024 + ch);
;       float x8[8]; unpack8(raw, x8);
;       const float4 w0 = *(const float4*)(conv_w + j * 1024 + ch), w1 = *(const float4*)(conv_w + j * 1024 + ch + 4);
; DI void mlstmA_item(const Params& p, char* lds, int item) {
;     ...
;     conv_unit(PM, p.in[5], p.in[6], b, c * 64 + t, 512 + hd * 128 + cgk * 8, 0.08838834764831845f, a8);
;     const float w = win[t];
; #pragma unroll
;     for (int e = 0; e < 8; ++e) KTs[(cgk * 8 + e) * 72 + t] = f2bf(a8[e] * w);
	v_mul_f32_e32 v188, v196, v188
	v_mul_f32_e32 v189, v196, v189
	v_mul_f32_e32 v190, v196, v190
	v_mul_f32_e32 v191, v196, v191
	v_mul_f32_e32 v192, v196, v192
	v_mul_f32_e32 v193, v196, v193
	v_mul_f32_e32 v194, v196, v194
	v_mul_f32_e32 v195, v196, v195
	v_cvt_pk_bf16_f32 v188, v188, s77
	v_cvt_pk_bf16_f32 v189, v189, s77
	v_cvt_pk_bf16_f32 v190, v190, s77
	v_cvt_pk_bf16_f32 v191, v191, s77
	v_cvt_pk_bf16_f32 v192, v192, s77
	v_cvt_pk_bf16_f32 v193, v193, s77
	v_cvt_pk_bf16_f32 v194, v194, s77
	v_cvt_pk_bf16_f32 v195, v195, s77
	ds_write_b16 v198, v188
	ds_write_b16 v198, v189 offset:144
	ds_write_b16 v198, v190 offset:288
	ds_write_b16 v198, v191 offset:432
	ds_write_b16 v198, v192 offset:576
	ds_write_b16 v198, v193 offset:720
	ds_write_b16 v198, v194 offset:864
	ds_write_b16 v198, v195 offset:1008
	s_add_i32 s97, s10, s70
	v_and_b32_e32 v70, 15, v222
	s_bfe_u32 s72, s97, 0x20007
	v_lshlrev_b32_e32 v70, 3, v70
	s_lshl_b32 s72, s72, 7
	v_add_u32_e32 v70, s72, v70
	s_ashr_i32 s74, s97, 9
	s_ashr_i32 s75, s74, 31
	s_lshl_b64 s[74:75], s[74:75], 24
	s_add_u32 s74, s74, s4
	s_addc_u32 s75, s75, s5
	v_lshlrev_b32_e32 v76, 1, v70
	v_mov_b32_e32 v77, 0
	v_lshl_add_u64 v[78:79], s[74:75], 0, v[76:77]
	s_and_b32 s76, s97, 0x7f
	s_lshl_b32 s76, s76, 6
	v_lshrrev_b32_e32 v75, 4, v222
	s_movk_i32 s77, 0x800
	v_add_u32_e32 v184, s76, v75
	v_add_u32_e32 v185, -1, v184
	v_mov_b32_e32 v114, 0
	v_mov_b32_e32 v115, 0
	v_mov_b32_e32 v116, 0
	v_mov_b32_e32 v117, 0
	v_mov_b32_e32 v118, 0
	v_mov_b32_e32 v119, 0
	v_mov_b32_e32 v120, 0
	v_mov_b32_e32 v121, 0
	v_mov_b32_e32 v122, 0
	v_mov_b32_e32 v123, 0
	v_mov_b32_e32 v124, 0
	v_mov_b32_e32 v125, 0
	v_mad_i64_i32 v[186:187], s[88:89], v185, s77, v[78:79]
	v_cmp_lt_i32_e64 s[84:85], 2, v184
	s_and_saveexec_b64 s[86:87], s[84:85]
	global_load_dwordx4 v[114:117], v[186:187], off offset:-3072
	s_or_b64 exec, exec, s[86:87]
	v_cmp_lt_i32_e64 s[84:85], 1, v184
	s_and_saveexec_b64 s[86:87], s[84:85]
	global_load_dwordx4 v[118:121], v[186:187], off offset:-1024
	s_or_b64 exec, exec, s[86:87]
	v_cmp_lt_i32_e64 s[84:85], 0, v184
	s_and_saveexec_b64 s[86:87], s[84:85]
	global_load_dwordx4 v[122:125], v[186:187], off offset:1024
	s_or_b64 exec, exec, s[86:87]
	global_load_dwordx4 v[126:129], v[186:187], off offset:3072
	v_add_u32_e32 v184, 32, v184
	v_add_u32_e32 v185, -1, v184
	v_mov_b32_e32 v130, 0
	v_mov_b32_e32 v131, 0
	v_mov_b32_e32 v132, 0
	v_mov_b32_e32 v133, 0
	v_mov_b32_e32 v134, 0
	v_mov_b32_e32 v135, 0
	v_mov_b32_e32 v136, 0
	v_mov_b32_e32 v137, 0
	v_mov_b32_e32 v172, 0
	v_mov_b32_e32 v173, 0
	v_mov_b32_e32 v174, 0
	v_mov_b32_e32 v175, 0
	v_mad_i64_i32 v[186:187], s[88:89], v185, s77, v[78:79]
	v_cmp_lt_i32_e64 s[84:85], 2, v184
	s_and_saveexec_b64 s[86:87], s[84:85]
	global_load_dwordx4 v[130:133], v[186:187], off offset:-3072
	s_or_b64 exec, exec, s[86:87]
	v_cmp_lt_i32_e64 s[84:85], 1, v184
	s_and_saveexec_b64 s[86:87], s[84:85]
	global_load_dwordx4 v[134:137], v[186:187], off offset:-1024
	s_or_b64 exec, exec, s[86:87]
	v_cmp_lt_i32_e64 s[84:85], 0, v184
	s_and_saveexec_b64 s[86:87], s[84:85]
	global_load_dwordx4 v[172:175], v[186:187], off offset:1024
	s_or_b64 exec, exec, s[86:87]
	global_load_dwordx4 v[176:179], v[186:187], off offset:3072

; DI unsigned pack2(float a, float b) { const f32x2 v = {a, b}; return __builtin_bit_cast(unsigned, __builtin_convertvector(v, bf16v2)); }
; DI float bflo(unsigned w) { return __uint_as_float(w << 16); }
; DI float bfhi(unsigned w) { return __uint_as_float(w & 0xffff0000u); }
; DI void mlstmC_pair(const Params& p, char* lds_all, int pair) {
;     ...
;   for (int tt = 0; tt < 2; ++tt) {
;     const int tq = tt * 32 + l31;
;     float t1 = 0.f, t2 = 0.f;
;     for (int e4 = 0; e4 < 4; ++e4) { t1 += red[(e4 * 64 + tq) * 2]; t2 += red[(e4 * 64 + tq) * 2 + 1]; }
;     const float mu = t1 * (1.f / 128.f);
;     const float var = fmaxf(t2 * (1.f / 128.f) - mu * mu, 0.f);
;     const float rstd = rsqrtf(var + LN_EPS);
;     const size_t row = (size_t)b * SEQ + c * 64 + tq;
; #pragma unroll
;     for (int g = 0; g < 4; ++g) {
;       const int e0 = et * 32 + 8 * g + 4 * hh;
;       const uint2 og = *(const uint2*)(PO + row * 512 + hd * 128 + e0);
;       const float4 gg = *(const float4*)(ng + e0);
;       const float o0 = __builtin_amdgcn_rcpf(1.f + __expf(-bflo(og.x))), o1 = __builtin_amdgcn_rcpf(1.f + __expf(-bfhi(og.x))), o2 = __builtin_amdgcn_rcpf(1.f + __expf(-bflo(og.y))), o3 = __builtin_amdgcn_rcpf(1.f + __expf(-bfhi(og.y)));
;       uint2 o;
;       o.x = pack2(o0 * (Hn[tt][4 * g] - mu) * rstd * gg.x, o1 * (Hn[tt][4 * g + 1] - mu) * rstd * gg.y);
;       o.y = pack2(o2 * (Hn[tt][4 * g + 2] - mu) * rstd * gg.z, o3 * (Hn[tt][4 * g + 3] - mu) * rstd * gg.w);
;       *(uint2*)(MIX + row * 1024 + 512 + hd * 128 + e0) = o;
;     }
.LBB0_569:
	s_or_b64 exec, exec, s[4:5]
	v_or_b32_e32 v74, v22, v36
	v_or_b32_e32 v75, v37, v54
	v_mov_b32_e32 v185, v23
	v_mov_b32_e32 v187, v23
	v_or_b32_e32 v184, v74, v53
	v_or_b32_e32 v186, v74, v52
	v_lshlrev_b64 v[184:185], 10, v[184:185]
	v_lshlrev_b64 v[186:187], 10, v[186:187]
	v_lshlrev_b32_e32 v76, 1, v47
	v_mov_b32_e32 v77, 0
	v_lshlrev_b32_e32 v78, 1, v75
	v_mov_b32_e32 v79, 0
	v_lshl_add_u64 v[188:189], s[74:75], 0, v[76:77]
	v_lshl_add_u64 v[188:189], v[188:189], 0, v[78:79]
	v_lshl_add_u64 v[184:185], v[188:189], 0, v[184:185]
	v_lshl_add_u64 v[186:187], v[188:189], 0, v[186:187]
	v_lshlrev_b32_e32 v76, 2, v47
	v_lshlrev_b32_e32 v78, 2, v75
	v_lshl_add_u64 v[190:191], s[38:39], 0, v[76:77]
	v_lshl_add_u64 v[190:191], v[190:191], 0, v[78:79]
	global_load_dwordx2 v[224:225], v[184:185], off
	global_load_dwordx4 v[240:243], v[190:191], off
	global_load_dwordx2 v[226:227], v[184:185], off offset:16
	global_load_dwordx4 v[244:247], v[190:191], off offset:32
	global_load_dwordx2 v[228:229], v[184:185], off offset:32
	global_load_dwordx4 v[212:215], v[190:191], off offset:64
	global_load_dwordx2 v[230:231], v[184:185], off offset:48
	global_load_dwordx4 v[216:219], v[190:191], off offset:96
	global_load_dwordx2 v[232:233], v[186:187], off
	global_load_dwordx2 v[234:235], v[186:187], off offset:16
	global_load_dwordx2 v[236:237], v[186:187], off offset:32
	global_load_dwordx2 v[238:239], v[186:187], off offset:48
	s_waitcnt lgkmcnt(1)
	v_lshl_add_u32 v10, v53, 3, v51
	s_waitcnt lgkmcnt(0)
	s_barrier
	v_add_u32_e32 v14, 0xfe00, v10
	ds_read_b64 v[10:11], v10 offset:65024
	ds_read2st64_b64 v[56:59], v14 offset0:1 offset1:2
	ds_read_b64 v[14:15], v14 offset:1536
	v_lshlrev_b32_e32 v20, 2, v47
	v_or_b32_e32 v55, v22, v36
	s_waitcnt lgkmcnt(2)
	v_pk_add_f32 v[10:11], v[10:11], 0 op_sel_hi:[1,0]
	v_lshl_add_u64 v[4:5], s[38:39], 0, v[20:21]
	s_waitcnt lgkmcnt(1)
	v_pk_add_f32 v[10:11], v[10:11], v[56:57]
	v_lshlrev_b32_e32 v20, 1, v47
	v_pk_add_f32 v[10:11], v[10:11], v[58:59]
	v_or_b32_e32 v22, v55, v53
	s_waitcnt lgkmcnt(0)
	v_pk_add_f32 v[10:11], v[10:11], v[14:15]
	v_lshl_add_u64 v[12:13], s[74:75], 0, v[20:21]
	v_pk_mul_f32 v[14:15], v[10:11], s[78:79] op_sel_hi:[1,0]
	v_or_b32_e32 v37, v37, v54
	v_fma_f32 v10, -v14, v14, v15
	v_max_f32_e32 v10, 0, v10
	v_add_f32_e32 v10, 0x3727c5ac, v10
	v_cmp_gt_f32_e32 vcc, s22, v10
	v_mul_f32_e32 v11, 0x4b800000, v10
	v_lshlrev_b32_e32 v58, 2, v37
	v_cndmask_b32_e32 v10, v10, v11, vcc
	v_rsq_f32_e32 v10, v10
	v_mov_b32_e32 v59, v21
	v_lshl_add_u64 v[4:5], v[4:5], 0, v[58:59]
	v_pk_add_f32 v[42:43], v[42:43], v[14:15] op_sel_hi:[1,0] neg_lo:[0,1] neg_hi:[0,1]
	v_mul_f32_e32 v11, 0x45800000, v10
	v_cndmask_b32_e32 v36, v10, v11, vcc
	v_lshlrev_b64 v[10:11], 10, v[22:23]
	v_lshl_add_u64 v[46:47], v[12:13], 0, v[10:11]
	v_lshlrev_b64 v[10:11], 11, v[22:23]
	v_lshl_add_u64 v[10:11], s[68:69], 0, v[10:11]
	v_lshl_add_u64 v[60:61], v[10:11], 0, v[20:21]
	v_lshlrev_b32_e32 v10, 1, v37
	v_mov_b32_e32 v11, v21
	v_lshl_add_u64 v[46:47], v[46:47], 0, v[10:11]
	v_sub_f32_e32 v38, v38, v14
	v_sub_f32_e32 v39, v39, v14
	v_sub_f32_e32 v40, v40, v14
	v_sub_f32_e32 v41, v41, v14
	v_sub_f32_e32 v32, v32, v14
	v_sub_f32_e32 v33, v33, v14
	v_sub_f32_e32 v34, v34, v14
	v_sub_f32_e32 v35, v35, v14
	v_sub_f32_e32 v24, v24, v14
	v_sub_f32_e32 v25, v25, v14
	s_add_i32 s27, s27, s70
	s_add_i32 s26, s26, s17
	s_add_i32 s16, s16, s17
	s_cmpk_lt_i32 s27, 0x800
	s_waitcnt vmcnt(11)
	v_lshlrev_b32_e32 v22, 16, v224
	v_mul_f32_e32 v22, 0xbfb8aa3b, v22
	v_exp_f32_e32 v22, v22
	s_nop 0
	v_add_f32_e32 v22, 1.0, v22
	v_rcp_f32_e32 v62, v22
	v_and_b32_e32 v22, 0xffff0000, v224
	v_mul_f32_e32 v22, 0xbfb8aa3b, v22
	v_exp_f32_e32 v22, v22
	s_nop 0
	v_add_f32_e32 v22, 1.0, v22
	v_rcp_f32_e32 v63, v22
	v_lshlrev_b32_e32 v22, 16, v225
	v_mul_f32_e32 v22, 0xbfb8aa3b, v22
	v_exp_f32_e32 v22, v22
	v_mul_f32_e32 v42, v42, v62
	v_mul_f32_e32 v43, v43, v63
	v_add_f32_e32 v22, 1.0, v22
	v_rcp_f32_e32 v64, v22
	v_and_b32_e32 v22, 0xffff0000, v225
	v_mul_f32_e32 v22, 0xbfb8aa3b, v22
	v_exp_f32_e32 v22, v22
	v_mul_f32_e32 v42, v42, v36
	v_mul_f32_e32 v43, v43, v36
	v_add_f32_e32 v22, 1.0, v22
	v_rcp_f32_e32 v65, v22
	s_waitcnt vmcnt(10)
	v_mul_f32_e32 v42, v240, v42
	v_mul_f32_e32 v43, v241, v43
	s_nop 0
	v_cvt_pk_bf16_f32 v56, v42, v43
	v_sub_f32_e32 v42, v44, v14
	v_sub_f32_e32 v43, v45, v14
	v_lshl_add_u64 v[44:45], v[60:61], 0, v[10:11]
	v_mul_f32_e32 v42, v42, v64
	v_mul_f32_e32 v43, v43, v65
	v_sub_f32_e32 v15, v27, v14
	v_sub_f32_e32 v14, v26, v14
	v_mul_f32_e32 v42, v42, v36
	v_mul_f32_e32 v43, v43, v36
	s_nop 0
	v_mul_f32_e32 v42, v242, v42
	v_mul_f32_e32 v43, v243, v43
	s_nop 0
	v_cvt_pk_bf16_f32 v57, v42, v43
	v_lshl_add_u64 v[42:43], v[44:45], 0, s[80:81]
	v_add_co_u32_e32 v44, vcc, s23, v44
	s_nop 1
	v_addc_co_u32_e32 v45, vcc, 0, v45, vcc
	global_store_dwordx2 v[44:45], v[56:57], off offset:1024
	s_waitcnt vmcnt(10)
	v_lshlrev_b32_e32 v22, 16, v226
	v_mul_f32_e32 v22, 0xbfb8aa3b, v22
	v_exp_f32_e32 v22, v22
	s_nop 0
	v_add_f32_e32 v22, 1.0, v22
	v_rcp_f32_e32 v60, v22
	v_and_b32_e32 v22, 0xffff0000, v226
	v_mul_f32_e32 v22, 0xbfb8aa3b, v22
	v_exp_f32_e32 v22, v22
	s_nop 0
	v_add_f32_e32 v22, 1.0, v22
	v_rcp_f32_e32 v61, v22
	v_lshlrev_b32_e32 v22, 16, v227
	v_mul_f32_e32 v22, 0xbfb8aa3b, v22
	v_exp_f32_e32 v22, v22
	v_mul_f32_e32 v38, v38, v60
	v_mul_f32_e32 v39, v39, v61
	v_add_f32_e32 v22, 1.0, v22
	v_rcp_f32_e32 v44, v22
	v_and_b32_e32 v22, 0xffff0000, v227
	v_mul_f32_e32 v22, 0xbfb8aa3b, v22
	v_exp_f32_e32 v22, v22
	v_mul_f32_e32 v38, v36, v38
	v_mul_f32_e32 v39, v36, v39
	v_add_f32_e32 v22, 1.0, v22
	v_rcp_f32_e32 v45, v22
	s_waitcnt vmcnt(9)
; DI unsigned pack2(float a, float b) { const f32x2 v = {a, b}; return __builtin_bit_cast(unsigned, __builtin_convertvector(v, bf16v2)); }
; DI float bflo(unsigned w) { return __uint_as_float(w << 16); }
; DI float bfhi(unsigned w) { return __uint_as_float(w & 0xffff0000u); }
; DI void mlstmC_pair(const Params& p, char* lds_all, int pair) {
;     ...
;   for (int tt = 0; tt < 2; ++tt) {
;     const int tq = tt * 32 + l31;
;     float t1 = 0.f, t2 = 0.f;
;     for (int e4 = 0; e4 < 4; ++e4) { t1 += red[(e4 * 64 + tq) * 2]; t2 += red[(e4 * 64 + tq) * 2 + 1]; }
;     const float mu = t1 * (1.f / 128.f);
;     const float var = fmaxf(t2 * (1.f / 128.f) - mu * mu, 0.f);
;     const float rstd = rsqrtf(var + LN_EPS);
;     const size_t row = (size_t)b * SEQ + c * 64 + tq;
; #pragma unroll
;     for (int g = 0; g < 4; ++g) {
;       const int e0 = et * 32 + 8 * g + 4 * hh;
;       const uint2 og = *(const uint2*)(PO + row * 512 + hd * 128 + e0);
;       const float4 gg = *(const float4*)(ng + e0);
;       const float o0 = __builtin_amdgcn_rcpf(1.f + __expf(-bflo(og.x))), o1 = __builtin_amdgcn_rcpf(1.f + __expf(-bfhi(og.x))), o2 = __builtin_amdgcn_rcpf(1.f + __expf(-bflo(og.y))), o3 = __builtin_amdgcn_rcpf(1.f + __expf(-bfhi(og.y)));
;       uint2 o;
;       o.x = pack2(o0 * (Hn[tt][4 * g] - mu) * rstd * gg.x, o1 * (Hn[tt][4 * g + 1] - mu) * rstd * gg.y);
;       o.y = pack2(o2 * (Hn[tt][4 * g + 2] - mu) * rstd * gg.z, o3 * (Hn[tt][4 * g + 3] - mu) * rstd * gg.w);
;       *(uint2*)(MIX + row * 1024 + 512 + hd * 128 + e0) = o;
;     }
	v_mul_f32_e32 v38, v244, v38
	v_mul_f32_e32 v39, v245, v39
	v_mul_f32_e32 v40, v40, v44
	v_mul_f32_e32 v41, v41, v45
	v_cvt_pk_bf16_f32 v38, v38, v39
	v_mul_f32_e32 v40, v36, v40
	v_mul_f32_e32 v41, v36, v41
	v_mul_f32_e32 v40, v246, v40
	v_mul_f32_e32 v41, v247, v41
	s_nop 0
	v_cvt_pk_bf16_f32 v39, v40, v41
	global_store_dwordx2 v[42:43], v[38:39], off offset:16
	s_waitcnt vmcnt(9)
	v_lshlrev_b32_e32 v22, 16, v228
	v_mul_f32_e32 v22, 0xbfb8aa3b, v22
	v_exp_f32_e32 v22, v22
	s_nop 0
	v_add_f32_e32 v22, 1.0, v22
	v_rcp_f32_e32 v44, v22
	v_and_b32_e32 v22, 0xffff0000, v228
	v_mul_f32_e32 v22, 0xbfb8aa3b, v22
	v_exp_f32_e32 v22, v22
	s_nop 0
	v_add_f32_e32 v22, 1.0, v22
	v_rcp_f32_e32 v45, v22
	v_lshlrev_b32_e32 v22, 16, v229
	v_mul_f32_e32 v22, 0xbfb8aa3b, v22
	v_exp_f32_e32 v22, v22
	v_mul_f32_e32 v32, v32, v44
	v_mul_f32_e32 v33, v33, v45
	v_add_f32_e32 v22, 1.0, v22
	v_rcp_f32_e32 v56, v22
	v_and_b32_e32 v22, 0xffff0000, v229
	v_mul_f32_e32 v22, 0xbfb8aa3b, v22
	v_exp_f32_e32 v22, v22
	v_mul_f32_e32 v32, v36, v32
	v_mul_f32_e32 v33, v36, v33
	v_add_f32_e32 v22, 1.0, v22
	v_rcp_f32_e32 v57, v22
	s_waitcnt vmcnt(8)
	v_mul_f32_e32 v32, v212, v32
	v_mul_f32_e32 v33, v213, v33
	v_mul_f32_e32 v34, v34, v56
	v_mul_f32_e32 v35, v35, v57
	v_cvt_pk_bf16_f32 v32, v32, v33
	v_mul_f32_e32 v34, v36, v34
	v_mul_f32_e32 v35, v36, v35
	v_mul_f32_e32 v34, v214, v34
	v_mul_f32_e32 v35, v215, v35
	s_nop 0
	v_cvt_pk_bf16_f32 v33, v34, v35
	s_waitcnt vmcnt(7)
	v_lshlrev_b32_e32 v22, 16, v230
	global_store_dwordx2 v[42:43], v[32:33], off offset:32
	v_mul_f32_e32 v22, 0xbfb8aa3b, v22
	v_exp_f32_e32 v22, v22
	s_nop 0
	v_add_f32_e32 v22, 1.0, v22
	v_rcp_f32_e32 v32, v22
	v_and_b32_e32 v22, 0xffff0000, v230
	v_mul_f32_e32 v22, 0xbfb8aa3b, v22
	v_exp_f32_e32 v22, v22
	s_nop 0
	v_add_f32_e32 v22, 1.0, v22
	v_rcp_f32_e32 v33, v22
	v_lshlrev_b32_e32 v22, 16, v231
	v_mul_f32_e32 v22, 0xbfb8aa3b, v22
	v_exp_f32_e32 v22, v22
	v_mul_f32_e32 v24, v24, v32
	v_mul_f32_e32 v25, v25, v33
	v_add_f32_e32 v22, 1.0, v22
	v_rcp_f32_e32 v34, v22
	v_and_b32_e32 v22, 0xffff0000, v231
	v_mul_f32_e32 v22, 0xbfb8aa3b, v22
	v_exp_f32_e32 v22, v22
	v_mul_f32_e32 v24, v36, v24
	v_mul_f32_e32 v25, v36, v25
	v_add_f32_e32 v22, 1.0, v22
	v_rcp_f32_e32 v35, v22
	s_waitcnt vmcnt(7)
	v_mul_f32_e32 v24, v216, v24
	v_mul_f32_e32 v25, v217, v25
	v_mul_f32_e32 v14, v14, v34
	v_mul_f32_e32 v15, v15, v35
	v_cvt_pk_bf16_f32 v24, v24, v25
	v_mul_f32_e32 v14, v36, v14
	v_mul_f32_e32 v15, v36, v15
	v_mul_f32_e32 v14, v218, v14
	v_mul_f32_e32 v15, v219, v15
	s_nop 0
	v_cvt_pk_bf16_f32 v25, v14, v15
	v_lshl_add_u32 v14, v52, 3, v51
	v_add_u32_e32 v22, 0xfe00, v14
	ds_read_b64 v[14:15], v14 offset:65024
	global_store_dwordx2 v[42:43], v[24:25], off offset:48
	ds_read2st64_b64 v[24:27], v22 offset0:1 offset1:2
	s_waitcnt lgkmcnt(1)
	v_add_f32_e32 v14, 0, v14
	v_add_f32_e32 v15, 0, v15
	s_waitcnt lgkmcnt(0)
	v_add_f32_e32 v14, v14, v24
	v_add_f32_e32 v15, v15, v25
	ds_read_b64 v[24:25], v22 offset:1536
	v_add_f32_e32 v14, v14, v26
	v_add_f32_e32 v15, v15, v27
	s_waitcnt lgkmcnt(0)
	v_add_f32_e32 v14, v14, v24
	v_add_f32_e32 v15, v15, v25
	s_nop 0
	v_mul_f32_e32 v14, s78, v14
	v_mul_f32_e32 v15, s78, v15
	s_nop 0
	v_fma_f32 v22, -v14, v14, v15
	v_max_f32_e32 v22, 0, v22
	v_add_f32_e32 v22, 0x3727c5ac, v22
	v_cmp_gt_f32_e32 vcc, s22, v22
	v_mul_f32_e32 v24, 0x4b800000, v22
	v_sub_f32_e32 v28, v28, v14
	v_sub_f32_e32 v29, v29, v14
	v_cndmask_b32_e32 v22, v22, v24, vcc
	v_rsq_f32_e32 v22, v22
	v_sub_f32_e32 v30, v30, v14
	v_sub_f32_e32 v31, v31, v14
	v_sub_f32_e32 v16, v16, v14
	v_sub_f32_e32 v17, v17, v14
	v_sub_f32_e32 v18, v18, v14
	v_sub_f32_e32 v19, v19, v14
	v_mul_f32_e32 v24, 0x45800000, v22
	v_cndmask_b32_e32 v24, v22, v24, vcc
	v_or_b32_e32 v22, v55, v52
	v_lshlrev_b64 v[26:27], 10, v[22:23]
	v_lshl_add_u64 v[12:13], v[12:13], 0, v[26:27]
	v_lshl_add_u64 v[12:13], v[12:13], 0, v[10:11]
	v_lshlrev_b64 v[22:23], 11, v[22:23]
	v_lshl_add_u64 v[22:23], s[68:69], 0, v[22:23]
	v_lshl_add_u64 v[22:23], v[22:23], 0, v[20:21]
	v_lshl_add_u64 v[22:23], v[22:23], 0, v[10:11]
	v_lshl_add_u64 v[10:11], v[22:23], 0, s[80:81]
	v_add_co_u32_e32 v22, vcc, s23, v22
	v_sub_f32_e32 v6, v6, v14
	v_sub_f32_e32 v7, v7, v14
	s_nop 0
	v_addc_co_u32_e32 v23, vcc, 0, v23, vcc
	v_sub_f32_e32 v8, v8, v14
	v_sub_f32_e32 v9, v9, v14
	v_sub_f32_e32 v0, v0, v14
	v_sub_f32_e32 v1, v1, v14
	v_sub_f32_e32 v2, v2, v14
	v_sub_f32_e32 v3, v3, v14
	s_waitcnt vmcnt(7)
; DI unsigned pack2(float a, float b) { const f32x2 v = {a, b}; return __builtin_bit_cast(unsigned, __builtin_convertvector(v, bf16v2)); }
; DI float bflo(unsigned w) { return __uint_as_float(w << 16); }
; DI float bfhi(unsigned w) { return __uint_as_float(w & 0xffff0000u); }
; DI void mlstmC_pair(const Params& p, char* lds_all, int pair) {
;     ...
;     for (int g = 0; g < 4; ++g) {
;       const int e0 = et * 32 + 8 * g + 4 * hh;
;       const uint2 og = *(const uint2*)(PO + row * 512 + hd * 128 + e0);
;       const float4 gg = *(const float4*)(ng + e0);
;       const float o0 = __builtin_amdgcn_rcpf(1.f + __expf(-bflo(og.x))), o1 = __builtin_amdgcn_rcpf(1.f + __expf(-bfhi(og.x))), o2 = __builtin_amdgcn_rcpf(1.f + __expf(-bflo(og.y))), o3 = __builtin_amdgcn_rcpf(1.f + __expf(-bfhi(og.y)));
;       uint2 o;
;       o.x = pack2(o0 * (Hn[tt][4 * g] - mu) * rstd * gg.x, o1 * (Hn[tt][4 * g + 1] - mu) * rstd * gg.y);
;       o.y = pack2(o2 * (Hn[tt][4 * g + 2] - mu) * rstd * gg.z, o3 * (Hn[tt][4 * g + 3] - mu) * rstd * gg.w);
;       *(uint2*)(MIX + row * 1024 + 512 + hd * 128 + e0) = o;
;     }
	v_lshlrev_b32_e32 v20, 16, v232
	v_mul_f32_e32 v20, 0xbfb8aa3b, v20
	v_exp_f32_e32 v20, v20
	s_nop 0
	v_add_f32_e32 v20, 1.0, v20
	v_rcp_f32_e32 v36, v20
	v_and_b32_e32 v20, 0xffff0000, v232
	v_mul_f32_e32 v20, 0xbfb8aa3b, v20
	v_exp_f32_e32 v20, v20
	s_nop 0
	v_add_f32_e32 v20, 1.0, v20
	v_rcp_f32_e32 v37, v20
	v_lshlrev_b32_e32 v20, 16, v233
	v_mul_f32_e32 v20, 0xbfb8aa3b, v20
	v_exp_f32_e32 v20, v20
	v_mul_f32_e32 v28, v28, v36
	v_mul_f32_e32 v29, v29, v37
	v_add_f32_e32 v20, 1.0, v20
	v_rcp_f32_e32 v26, v20
	v_and_b32_e32 v20, 0xffff0000, v233
	v_mul_f32_e32 v20, 0xbfb8aa3b, v20
	v_exp_f32_e32 v20, v20
	v_mul_f32_e32 v28, v28, v24
	v_mul_f32_e32 v29, v29, v24
	v_add_f32_e32 v20, 1.0, v20
	v_rcp_f32_e32 v27, v20
	v_mul_f32_e32 v28, v240, v28
	v_mul_f32_e32 v29, v241, v29
	v_mul_f32_e32 v26, v30, v26
	v_mul_f32_e32 v27, v31, v27
	s_nop 0
	v_mul_f32_e32 v26, v26, v24
	v_mul_f32_e32 v27, v27, v24
	v_cvt_pk_bf16_f32 v28, v28, v29
	v_mul_f32_e32 v26, v242, v26
	v_mul_f32_e32 v27, v243, v27
	s_nop 0
	v_cvt_pk_bf16_f32 v29, v26, v27
	global_store_dwordx2 v[22:23], v[28:29], off offset:1024
	s_waitcnt vmcnt(7)
	v_lshlrev_b32_e32 v20, 16, v234
	v_mul_f32_e32 v20, 0xbfb8aa3b, v20
	v_exp_f32_e32 v20, v20
	s_nop 0
	v_add_f32_e32 v20, 1.0, v20
	v_rcp_f32_e32 v30, v20
	v_and_b32_e32 v20, 0xffff0000, v234
	v_mul_f32_e32 v20, 0xbfb8aa3b, v20
	v_exp_f32_e32 v20, v20
	s_nop 0
	v_add_f32_e32 v20, 1.0, v20
	v_rcp_f32_e32 v31, v20
	v_lshlrev_b32_e32 v20, 16, v235
	v_mul_f32_e32 v20, 0xbfb8aa3b, v20
	v_exp_f32_e32 v20, v20
	v_mul_f32_e32 v16, v16, v30
	v_mul_f32_e32 v17, v17, v31
	v_add_f32_e32 v20, 1.0, v20
	v_rcp_f32_e32 v22, v20
	v_and_b32_e32 v20, 0xffff0000, v235
	v_mul_f32_e32 v20, 0xbfb8aa3b, v20
	v_exp_f32_e32 v20, v20
	v_mul_f32_e32 v16, v24, v16
	v_mul_f32_e32 v17, v24, v17
	v_add_f32_e32 v20, 1.0, v20
	v_rcp_f32_e32 v23, v20
	v_mul_f32_e32 v16, v244, v16
	v_mul_f32_e32 v17, v245, v17
	v_mul_f32_e32 v18, v18, v22
	v_mul_f32_e32 v19, v19, v23
	v_cvt_pk_bf16_f32 v16, v16, v17
	v_mul_f32_e32 v18, v24, v18
	v_mul_f32_e32 v19, v24, v19
	v_mul_f32_e32 v18, v246, v18
	v_mul_f32_e32 v19, v247, v19
	s_nop 0
	v_cvt_pk_bf16_f32 v17, v18, v19
	global_store_dwordx2 v[10:11], v[16:17], off offset:16
	s_waitcnt vmcnt(7)
	v_lshlrev_b32_e32 v18, 16, v236
	v_and_b32_e32 v16, 0xffff0000, v236
	v_mul_f32_e32 v16, 0xbfb8aa3b, v16
	v_exp_f32_e32 v16, v16
	v_mul_f32_e32 v18, 0xbfb8aa3b, v18
	v_exp_f32_e32 v18, v18
	v_add_f32_e32 v16, 1.0, v16
	v_rcp_f32_e32 v23, v16
	v_lshlrev_b32_e32 v16, 16, v237
	v_mul_f32_e32 v16, 0xbfb8aa3b, v16
	v_exp_f32_e32 v16, v16
	v_add_f32_e32 v18, 1.0, v18
	v_rcp_f32_e32 v22, v18
	v_add_f32_e32 v16, 1.0, v16
	v_rcp_f32_e32 v26, v16
	v_and_b32_e32 v16, 0xffff0000, v237
	v_mul_f32_e32 v16, 0xbfb8aa3b, v16
	v_exp_f32_e32 v16, v16
	v_mul_f32_e32 v6, v6, v22
	v_mul_f32_e32 v7, v7, v23
	v_add_f32_e32 v16, 1.0, v16
	v_rcp_f32_e32 v27, v16
	v_mul_f32_e32 v6, v24, v6
	v_mul_f32_e32 v7, v24, v7
	v_mul_f32_e32 v8, v8, v26
	v_mul_f32_e32 v9, v9, v27
	s_nop 0
	v_mul_f32_e32 v8, v24, v8
	v_mul_f32_e32 v9, v24, v9
	v_mul_f32_e32 v6, v212, v6
	v_mul_f32_e32 v7, v213, v7
	v_mul_f32_e32 v8, v214, v8
	v_mul_f32_e32 v9, v215, v9
	v_cvt_pk_bf16_f32 v6, v6, v7
	v_cvt_pk_bf16_f32 v7, v8, v9
	s_nop 0
	global_store_dwordx2 v[10:11], v[6:7], off offset:32
	s_waitcnt vmcnt(7)
	v_lshlrev_b32_e32 v6, 16, v238
	v_and_b32_e32 v7, 0xffff0000, v238
	v_lshlrev_b32_e32 v8, 16, v239
	v_and_b32_e32 v9, 0xffff0000, v239
	v_mul_f32_e32 v6, 0xbfb8aa3b, v6
	v_mul_f32_e32 v7, 0xbfb8aa3b, v7
	v_mul_f32_e32 v8, 0xbfb8aa3b, v8
	v_mul_f32_e32 v9, 0xbfb8aa3b, v9
	v_exp_f32_e32 v6, v6
	v_exp_f32_e32 v7, v7
	v_exp_f32_e32 v8, v8
	v_exp_f32_e32 v9, v9
	v_add_f32_e32 v6, 1.0, v6
	v_add_f32_e32 v7, 1.0, v7
	v_add_f32_e32 v8, 1.0, v8
	v_add_f32_e32 v9, 1.0, v9
	v_rcp_f32_e32 v6, v6
	v_rcp_f32_e32 v7, v7
	v_rcp_f32_e32 v8, v8
	v_rcp_f32_e32 v9, v9
	v_mul_f32_e32 v0, v0, v6
	v_mul_f32_e32 v1, v1, v7
	s_nop 0
	v_mul_f32_e32 v0, v24, v0
	v_mul_f32_e32 v1, v24, v1
	v_mul_f32_e32 v2, v2, v8
	v_mul_f32_e32 v3, v3, v9
	v_mul_f32_e32 v0, v216, v0
	v_mul_f32_e32 v1, v217, v1
	v_mul_f32_e32 v2, v24, v2
	v_mul_f32_e32 v3, v24, v3
	v_mul_f32_e32 v2, v218, v2
	v_mul_f32_e32 v3, v219, v3
	v_cvt_pk_bf16_f32 v0, v0, v1
	v_cvt_pk_bf16_f32 v1, v2, v3
	global_store_dwordx2 v[10:11], v[0:1], off offset:48
	s_barrier
	s_cbranch_scc0 .LBB0_626

; DI unsigned pack2(float a, float b) { const f32x2 v = {a, b}; return __builtin_bit_cast(unsigned, __builtin_convertvector(v, bf16v2)); }
; DI void conv_unit(const u16* __restrict__ PM, const float* __restrict__ conv_w, const float* __restrict__ conv_b, int b, int sl0, int ch, float scale, float* a8) {
;   { const float4 b0 = *(const float4*)(conv_b + ch), b1 = *(const float4*)(conv_b + ch + 4); a8[0] = b0.x; a8[1] = b0.y; a8[2] = b0.z; a8[3] = b0.w; a8[4] = b1.x; a8[5] = b1.y; a8[6] = b1.z; a8[7] = b1.w; }
; #pragma unroll
;   for (int j = 0; j < 4; ++j) {
;     const int sl = sl0 - 3 + j;
;     if (sl >= 0) {
;       const uint4 raw = *(const uint4*)(PM + ((size_t)b * SEQ + sl) * 1024 + ch);
;       float x8[8]; unpack8(raw, x8);
;       const float4 w0 = *(const float4*)(conv_w + j * 1024 + ch), w1 = *(const float4*)(conv_w + j * 1024 + ch + 4);
;       a8[0] += w0.x * x8[0]; a8[1] += w0.y * x8[1]; a8[2] += w0.z * x8[2]; a8[3] += w0.w * x8[3];
;       a8[4] += w1.x * x8[4]; a8[5] += w1.y * x8[5]; a8[6] += w1.z * x8[6]; a8[7] += w1.w * x8[7];
;     }
;   }
; DI void mlstmC_pair(const Params& p, char* lds_all, int pair) {
;     ...
; #pragma unroll 1
;   for (int i = 0; i < 8; ++i) {
;     const int cg8 = ltid & 31, isK = cg8 >> 4, chl = (cg8 & 15) * 8, t = (ltid >> 5) + 8 * i;
;     float a8[8];
;     conv_unit(PM, p.in[5], p.in[6], b, c * 64 + t, (isK ? 512 : 0) + hd * 128 + chl, isK ? 0.08838834764831845f : 1.f, a8);
;     uint4 o; o.x = pack2(a8[0], a8[1]); o.y = pack2(a8[2], a8[3]); o.z = pack2(a8[4], a8[5]); o.w = pack2(a8[6], a8[7]);
;     *(uint4*)((isK ? Ks : Qs) + t * 136 + chl) = o;
;   }
.LBB0_572:
	s_or_b64 exec, exec, s[0:1]
	v_ashrrev_i32_e32 v16, 9, v45
	v_bfe_u32 v44, v45, 7, 2
	v_lshlrev_b32_e32 v52, 3, v46
	v_and_b32_e32 v26, 16, v46
	v_lshlrev_b32_e32 v47, 7, v44
	v_and_b32_e32 v33, 0x78, v52
	v_lshlrev_b32_e32 v36, 5, v26
	v_ashrrev_i32_e32 v17, 31, v16
	v_or3_b32 v2, v47, v36, v33
	v_lshlrev_b64 v[34:35], 24, v[16:17]
	v_lshl_add_u64 v[0:1], s[40:41], 0, v[34:35]
	v_lshlrev_b32_e32 v20, 1, v2
	v_lshl_add_u64 v[18:19], v[0:1], 0, v[20:21]
	v_lshlrev_b32_e32 v20, 2, v2
	v_lshl_add_u64 v[22:23], s[62:63], 0, v[20:21]
	s_mov_b64 s[0:1], 0x3000
	v_lshl_add_u64 v[12:13], v[22:23], 0, s[0:1]
	s_movk_i32 s0, 0x3000
	v_add_co_u32_e64 v8, s[0:1], s0, v22
	global_load_dwordx4 v[0:3], v20, s[64:65] offset:16
	global_load_dwordx4 v[4:7], v20, s[64:65]
	v_addc_co_u32_e64 v9, s[0:1], 0, v23, s[0:1]
	global_load_dwordx4 v[8:11], v[8:9], off
	s_nop 0
	global_load_dwordx4 v[12:15], v[12:13], off offset:16
	s_mov_b32 s0, 0x11000
	v_mad_i32_i24 v51, v32, s0, 0
	v_add_u32_e32 v20, 0x4400, v51
	v_bfe_u32 v38, v46, 5, 3
	v_cmp_eq_u32_e64 s[0:1], 0, v26
	v_and_b32_e32 v40, 15, v46
	v_add_u32_e32 v32, s16, v32
	v_lshrrev_b32_e32 v37, 8, v46
	v_cndmask_b32_e64 v20, v20, v51, s[0:1]
	v_mul_u32_u24_e32 v39, 0x110, v38
	v_lshlrev_b32_e32 v40, 4, v40
	v_and_b32_e32 v32, 0x180, v32
	v_add3_u32 v54, v39, v40, v20
	v_add_u16_e32 v20, s26, v37
	v_or3_b32 v32, v36, v32, v33
	v_and_b32_e32 v20, 0x7f, v20
	v_lshl_or_b32 v34, v32, 1, v34
	v_lshlrev_b32_e32 v32, 11, v38
	v_cndmask_b32_e64 v26, v48, 1.0, s[0:1]
	s_mov_b64 s[0:1], 0x1000
	v_lshl_or_b32 v55, v20, 6, v38
	v_lshl_or_b32 v20, v20, 17, v32
	v_lshl_add_u64 v[28:29], v[22:23], 0, s[0:1]
	s_mov_b64 s[0:1], 0x2000
	v_lshl_add_u64 v[32:33], v[34:35], 0, v[20:21]
	v_and_b32_e32 v42, 0xff, v46
	s_mov_b32 s2, 0
	v_lshl_add_u64 v[30:31], v[22:23], 0, s[0:1]
	v_mov_b32_e32 v27, v26
	v_lshl_add_u64 v[32:33], s[76:77], 0, v[32:33]
	global_load_dwordx4 v[94:97], v[22:23], off
	global_load_dwordx4 v[98:101], v[22:23], off offset:16
	global_load_dwordx4 v[102:105], v[28:29], off
	global_load_dwordx4 v[106:109], v[28:29], off offset:16
	global_load_dwordx4 v[110:113], v[30:31], off
	global_load_dwordx4 v[114:117], v[30:31], off offset:16
	s_movk_i32 s2, 0x800
	v_mov_b32_e32 v184, v55
	v_add_u32_e32 v185, -1, v184
	v_mov_b32_e32 v118, 0
	v_mov_b32_e32 v119, 0
	v_mov_b32_e32 v120, 0
	v_mov_b32_e32 v121, 0
	v_mov_b32_e32 v122, 0
	v_mov_b32_e32 v123, 0
	v_mov_b32_e32 v124, 0
	v_mov_b32_e32 v125, 0
	v_mov_b32_e32 v126, 0
	v_mov_b32_e32 v127, 0
	v_mov_b32_e32 v128, 0
	v_mov_b32_e32 v129, 0
	v_mad_i64_i32 v[186:187], s[0:1], v185, s2, v[18:19]
	v_cmp_lt_u32_e64 s[0:1], 2, v184
	s_and_saveexec_b64 s[4:5], s[0:1]
	global_load_dwordx4 v[118:121], v[186:187], off offset:-4096
	s_or_b64 exec, exec, s[4:5]
	v_cmp_lt_u32_e64 s[0:1], 1, v184
	s_and_saveexec_b64 s[4:5], s[0:1]
	global_load_dwordx4 v[122:125], v[186:187], off offset:-2048
	s_or_b64 exec, exec, s[4:5]
	v_cmp_ne_u32_e64 s[0:1], 0, v184
	s_and_saveexec_b64 s[4:5], s[0:1]
	global_load_dwordx4 v[126:129], v[186:187], off
	s_or_b64 exec, exec, s[4:5]
	global_load_dwordx4 v[130:133], v[186:187], off offset:2048
	v_add_u32_e32 v184, 8, v55
	v_add_u32_e32 v185, -1, v184
	v_mov_b32_e32 v134, 0
	v_mov_b32_e32 v135, 0
	v_mov_b32_e32 v136, 0
	v_mov_b32_e32 v137, 0
	v_mov_b32_e32 v138, 0
	v_mov_b32_e32 v139, 0
	v_mov_b32_e32 v140, 0
	v_mov_b32_e32 v141, 0
	v_mov_b32_e32 v142, 0
	v_mov_b32_e32 v143, 0
	v_mov_b32_e32 v144, 0
	v_mov_b32_e32 v145, 0
	v_mad_i64_i32 v[186:187], s[0:1], v185, s2, v[18:19]
	v_cmp_lt_u32_e64 s[0:1], 2, v184
	s_and_saveexec_b64 s[4:5], s[0:1]
	global_load_dwordx4 v[134:137], v[186:187], off offset:-4096
	s_or_b64 exec, exec, s[4:5]
	v_cmp_lt_u32_e64 s[0:1], 1, v184
	s_and_saveexec_b64 s[4:5], s[0:1]
	global_load_dwordx4 v[138:141], v[186:187], off offset:-2048
	s_or_b64 exec, exec, s[4:5]
	v_cmp_ne_u32_e64 s[0:1], 0, v184
	s_and_saveexec_b64 s[4:5], s[0:1]
	global_load_dwordx4 v[142:145], v[186:187], off
	s_or_b64 exec, exec, s[4:5]
	global_load_dwordx4 v[146:149], v[186:187], off offset:2048
	v_add_u32_e32 v184, 16, v55
	v_add_u32_e32 v185, -1, v184
	v_mov_b32_e32 v150, 0
	v_mov_b32_e32 v151, 0
	v_mov_b32_e32 v152, 0
	v_mov_b32_e32 v153, 0
	v_mov_b32_e32 v154, 0
	v_mov_b32_e32 v155, 0
	v_mov_b32_e32 v156, 0
	v_mov_b32_e32 v157, 0
	v_mov_b32_e32 v158, 0
	v_mov_b32_e32 v159, 0
	v_mov_b32_e32 v160, 0
	v_mov_b32_e32 v161, 0
	v_mad_i64_i32 v[186:187], s[0:1], v185, s2, v[18:19]
	v_cmp_lt_u32_e64 s[0:1], 2, v184
	s_and_saveexec_b64 s[4:5], s[0:1]
	global_load_dwordx4 v[150:153], v[186:187], off offset:-4096
	s_or_b64 exec, exec, s[4:5]
	v_cmp_lt_u32_e64 s[0:1], 1, v184
	s_and_saveexec_b64 s[4:5], s[0:1]
	global_load_dwordx4 v[154:157], v[186:187], off offset:-2048
	s_or_b64 exec, exec, s[4:5]
	v_cmp_ne_u32_e64 s[0:1], 0, v184
	s_and_saveexec_b64 s[4:5], s[0:1]
	global_load_dwordx4 v[158:161], v[186:187], off
	s_or_b64 exec, exec, s[4:5]
	global_load_dwordx4 v[162:165], v[186:187], off offset:2048
	v_add_u32_e32 v184, 24, v55
	v_add_u32_e32 v185, -1, v184
	v_mov_b32_e32 v166, 0
	v_mov_b32_e32 v167, 0
	v_mov_b32_e32 v168, 0
	v_mov_b32_e32 v169, 0
	v_mov_b32_e32 v170, 0
	v_mov_b32_e32 v171, 0
	v_mov_b32_e32 v172, 0
	v_mov_b32_e32 v173, 0
	v_mov_b32_e32 v174, 0
	v_mov_b32_e32 v175, 0
	v_mov_b32_e32 v176, 0
	v_mov_b32_e32 v177, 0
	v_mad_i64_i32 v[186:187], s[0:1], v185, s2, v[18:19]
	v_cmp_lt_u32_e64 s[0:1], 2, v184
	s_and_saveexec_b64 s[4:5], s[0:1]
	global_load_dwordx4 v[166:169], v[186:187], off offset:-4096
	s_or_b64 exec, exec, s[4:5]
	v_cmp_lt_u32_e64 s[0:1], 1, v184
	s_and_saveexec_b64 s[4:5], s[0:1]
	global_load_dwordx4 v[170:173], v[186:187], off offset:-2048
	s_or_b64 exec, exec, s[4:5]
	v_cmp_ne_u32_e64 s[0:1], 0, v184
	s_and_saveexec_b64 s[4:5], s[0:1]
	global_load_dwordx4 v[174:177], v[186:187], off
	s_or_b64 exec, exec, s[4:5]
	global_load_dwordx4 v[178:181], v[186:187], off offset:2048
	s_waitcnt vmcnt(12)
; DI unsigned pack2(float a, float b) { const f32x2 v = {a, b}; return __builtin_bit_cast(unsigned, __builtin_convertvector(v, bf16v2)); }
; DI void conv_unit(const u16* __restrict__ PM, const float* __restrict__ conv_w, const float* __restrict__ conv_b, int b, int sl0, int ch, float scale, float* a8) {
;   { const float4 b0 = *(const float4*)(conv_b + ch), b1 = *(const float4*)(conv_b + ch + 4); a8[0] = b0.x; a8[1] = b0.y; a8[2] = b0.z; a8[3] = b0.w; a8[4] = b1.x; a8[5] = b1.y; a8[6] = b1.z; a8[7] = b1.w; }
; #pragma unroll
;   for (int j = 0; j < 4; ++j) {
;     const int sl = sl0 - 3 + j;
;     if (sl >= 0) {
;       const uint4 raw = *(const uint4*)(PM + ((size_t)b * SEQ + sl) * 1024 + ch);
;       float x8[8]; unpack8(raw, x8);
;       const float4 w0 = *(const float4*)(conv_w + j * 1024 + ch), w1 = *(const float4*)(conv_w + j * 1024 + ch + 4);
;       a8[0] += w0.x * x8[0]; a8[1] += w0.y * x8[1]; a8[2] += w0.z * x8[2]; a8[3] += w0.w * x8[3];
;       a8[4] += w1.x * x8[4]; a8[5] += w1.y * x8[5]; a8[6] += w1.z * x8[6]; a8[7] += w1.w * x8[7];
;     }
;   }
; #pragma unroll
;   for (int e = 0; e < 8; ++e) { const float v = a8[e]; a8[e] = scale * v * __builtin_amdgcn_rcpf(1.f + __expf(-v)); }
; DI void mlstmC_pair(const Params& p, char* lds_all, int pair) {
;     ...
; #pragma unroll 1
;   for (int i = 0; i < 8; ++i) {
;     const int cg8 = ltid & 31, isK = cg8 >> 4, chl = (cg8 & 15) * 8, t = (ltid >> 5) + 8 * i;
;     float a8[8];
;     conv_unit(PM, p.in[5], p.in[6], b, c * 64 + t, (isK ? 512 : 0) + hd * 128 + chl, isK ? 0.08838834764831845f : 1.f, a8);
;     uint4 o; o.x = pack2(a8[0], a8[1]); o.y = pack2(a8[2], a8[3]); o.z = pack2(a8[4], a8[5]); o.w = pack2(a8[6], a8[7]);
;     *(uint4*)((isK ? Ks : Qs) + t * 136 + chl) = o;
;   }
	v_lshlrev_b32_e32 v188, 16, v118
	v_and_b32_e32 v189, 0xffff0000, v118
	v_lshlrev_b32_e32 v190, 16, v119
	v_and_b32_e32 v191, 0xffff0000, v119
	v_lshlrev_b32_e32 v192, 16, v120
	v_and_b32_e32 v193, 0xffff0000, v120
	v_lshlrev_b32_e32 v194, 16, v121
	v_and_b32_e32 v195, 0xffff0000, v121
	v_fma_f32 v204, v94, v188, v4
	v_fma_f32 v205, v95, v189, v5
	v_fma_f32 v206, v96, v190, v6
	v_fma_f32 v207, v97, v191, v7
	v_fma_f32 v208, v98, v192, v0
	v_fma_f32 v209, v99, v193, v1
	v_fma_f32 v210, v100, v194, v2
	v_fma_f32 v211, v101, v195, v3
	v_lshlrev_b32_e32 v188, 16, v122
	v_and_b32_e32 v189, 0xffff0000, v122
	v_lshlrev_b32_e32 v190, 16, v123
	v_and_b32_e32 v191, 0xffff0000, v123
	v_lshlrev_b32_e32 v192, 16, v124
	v_and_b32_e32 v193, 0xffff0000, v124
	v_lshlrev_b32_e32 v194, 16, v125
	v_and_b32_e32 v195, 0xffff0000, v125
	v_fmac_f32_e32 v204, v102, v188
	v_fmac_f32_e32 v205, v103, v189
	v_fmac_f32_e32 v206, v104, v190
	v_fmac_f32_e32 v207, v105, v191
	v_fmac_f32_e32 v208, v106, v192
	v_fmac_f32_e32 v209, v107, v193
	v_fmac_f32_e32 v210, v108, v194
	v_fmac_f32_e32 v211, v109, v195
	v_lshlrev_b32_e32 v188, 16, v126
	v_and_b32_e32 v189, 0xffff0000, v126
	v_lshlrev_b32_e32 v190, 16, v127
	v_and_b32_e32 v191, 0xffff0000, v127
	v_lshlrev_b32_e32 v192, 16, v128
	v_and_b32_e32 v193, 0xffff0000, v128
	v_lshlrev_b32_e32 v194, 16, v129
	v_and_b32_e32 v195, 0xffff0000, v129
	v_fmac_f32_e32 v204, v110, v188
	v_fmac_f32_e32 v205, v111, v189
	v_fmac_f32_e32 v206, v112, v190
	v_fmac_f32_e32 v207, v113, v191
	v_fmac_f32_e32 v208, v114, v192
	v_fmac_f32_e32 v209, v115, v193
	v_fmac_f32_e32 v210, v116, v194
	v_fmac_f32_e32 v211, v117, v195
	v_lshlrev_b32_e32 v188, 16, v130
	v_and_b32_e32 v189, 0xffff0000, v130
	v_lshlrev_b32_e32 v190, 16, v131
	v_and_b32_e32 v191, 0xffff0000, v131
	v_lshlrev_b32_e32 v192, 16, v132
	v_and_b32_e32 v193, 0xffff0000, v132
	v_lshlrev_b32_e32 v194, 16, v133
	v_and_b32_e32 v195, 0xffff0000, v133
	v_fmac_f32_e32 v204, v8, v188
	v_fmac_f32_e32 v205, v9, v189
	v_fmac_f32_e32 v206, v10, v190
	v_fmac_f32_e32 v207, v11, v191
	v_fmac_f32_e32 v208, v12, v192
	v_fmac_f32_e32 v209, v13, v193
	v_fmac_f32_e32 v210, v14, v194
	v_fmac_f32_e32 v211, v15, v195
	v_mul_f32_e32 v212, 0xbfb8aa3b, v204
	v_mul_f32_e32 v213, 0xbfb8aa3b, v205
	v_mul_f32_e32 v214, 0xbfb8aa3b, v206
	v_mul_f32_e32 v215, 0xbfb8aa3b, v207
	v_mul_f32_e32 v216, 0xbfb8aa3b, v208
	v_mul_f32_e32 v217, 0xbfb8aa3b, v209
	v_mul_f32_e32 v218, 0xbfb8aa3b, v210
	v_mul_f32_e32 v219, 0xbfb8aa3b, v211
	v_mul_f32_e32 v188, v26, v204
	v_mul_f32_e32 v189, v27, v205
	v_mul_f32_e32 v190, v26, v206
	v_mul_f32_e32 v191, v27, v207
	v_mul_f32_e32 v192, v26, v208
	v_mul_f32_e32 v193, v27, v209
	v_mul_f32_e32 v194, v26, v210
	v_mul_f32_e32 v195, v27, v211
	v_exp_f32_e32 v212, v212
	v_exp_f32_e32 v213, v213
	v_exp_f32_e32 v214, v214
	v_exp_f32_e32 v215, v215
	v_exp_f32_e32 v216, v216
	v_exp_f32_e32 v217, v217
	v_exp_f32_e32 v218, v218
	v_exp_f32_e32 v219, v219
	v_add_f32_e32 v212, 1.0, v212
	v_add_f32_e32 v213, 1.0, v213
	v_add_f32_e32 v214, 1.0, v214
	v_add_f32_e32 v215, 1.0, v215
	v_add_f32_e32 v216, 1.0, v216
	v_add_f32_e32 v217, 1.0, v217
	v_add_f32_e32 v218, 1.0, v218
	v_add_f32_e32 v219, 1.0, v219
	v_rcp_f32_e32 v212, v212
	v_rcp_f32_e32 v213, v213
	v_rcp_f32_e32 v214, v214
	v_rcp_f32_e32 v215, v215
	v_rcp_f32_e32 v216, v216
	v_rcp_f32_e32 v217, v217
	v_rcp_f32_e32 v218, v218
	v_rcp_f32_e32 v219, v219
	v_mul_f32_e32 v188, v188, v212
	v_mul_f32_e32 v189, v189, v213
	v_mul_f32_e32 v190, v190, v214
	v_mul_f32_e32 v191, v191, v215
	v_mul_f32_e32 v192, v192, v216
	v_mul_f32_e32 v193, v193, v217
	v_mul_f32_e32 v194, v194, v218
	v_mul_f32_e32 v195, v195, v219
	v_cvt_pk_bf16_f32 v196, v188, v189
	v_cvt_pk_bf16_f32 v197, v190, v191
	v_cvt_pk_bf16_f32 v198, v192, v193
	v_cvt_pk_bf16_f32 v199, v194, v195
	ds_write_b128 v54, v[196:199]
	v_add_u32_e32 v184, 32, v55
	v_add_u32_e32 v185, -1, v184
	v_mov_b32_e32 v118, 0
	v_mov_b32_e32 v119, 0
	v_mov_b32_e32 v120, 0
	v_mov_b32_e32 v121, 0
	v_mov_b32_e32 v122, 0
	v_mov_b32_e32 v123, 0
	v_mov_b32_e32 v124, 0
	v_mov_b32_e32 v125, 0
	v_mov_b32_e32 v126, 0
	v_mov_b32_e32 v127, 0
	v_mov_b32_e32 v128, 0
	v_mov_b32_e32 v129, 0
	v_mad_i64_i32 v[186:187], s[0:1], v185, s2, v[18:19]
	v_cmp_lt_u32_e64 s[0:1], 2, v184
	s_and_saveexec_b64 s[4:5], s[0:1]
	global_load_dwordx4 v[118:121], v[186:187], off offset:-4096
	s_or_b64 exec, exec, s[4:5]
	v_cmp_lt_u32_e64 s[0:1], 1, v184
	s_and_saveexec_b64 s[4:5], s[0:1]
	global_load_dwordx4 v[122:125], v[186:187], off offset:-2048
	s_or_b64 exec, exec, s[4:5]
	v_cmp_ne_u32_e64 s[0:1], 0, v184
	s_and_saveexec_b64 s[4:5], s[0:1]
	global_load_dwordx4 v[126:129], v[186:187], off
	s_or_b64 exec, exec, s[4:5]
	global_load_dwordx4 v[130:133], v[186:187], off offset:2048
	s_waitcnt vmcnt(12)
; DI unsigned pack2(float a, float b) { const f32x2 v = {a, b}; return __builtin_bit_cast(unsigned, __builtin_convertvector(v, bf16v2)); }
; DI void conv_unit(const u16* __restrict__ PM, const float* __restrict__ conv_w, const float* __restrict__ conv_b, int b, int sl0, int ch, float scale, float* a8) {
;   { const float4 b0 = *(const float4*)(conv_b + ch), b1 = *(const float4*)(conv_b + ch + 4); a8[0] = b0.x; a8[1] = b0.y; a8[2] = b0.z; a8[3] = b0.w; a8[4] = b1.x; a8[5] = b1.y; a8[6] = b1.z; a8[7] = b1.w; }
; #pragma unroll
;   for (int j = 0; j < 4; ++j) {
;     const int sl = sl0 - 3 + j;
;     if (sl >= 0) {
;       const uint4 raw = *(const uint4*)(PM + ((size_t)b * SEQ + sl) * 1024 + ch);
;       float x8[8]; unpack8(raw, x8);
;       const float4 w0 = *(const float4*)(conv_w + j * 1024 + ch), w1 = *(const float4*)(conv_w + j * 1024 + ch + 4);
;       a8[0] += w0.x * x8[0]; a8[1] += w0.y * x8[1]; a8[2] += w0.z * x8[2]; a8[3] += w0.w * x8[3];
;       a8[4] += w1.x * x8[4]; a8[5] += w1.y * x8[5]; a8[6] += w1.z * x8[6]; a8[7] += w1.w * x8[7];
;     }
;   }
; #pragma unroll
;   for (int e = 0; e < 8; ++e) { const float v = a8[e]; a8[e] = scale * v * __builtin_amdgcn_rcpf(1.f + __expf(-v)); }
; DI void mlstmC_pair(const Params& p, char* lds_all, int pair) {
;     ...
; #pragma unroll 1
;   for (int i = 0; i < 8; ++i) {
;     const int cg8 = ltid & 31, isK = cg8 >> 4, chl = (cg8 & 15) * 8, t = (ltid >> 5) + 8 * i;
;     float a8[8];
;     conv_unit(PM, p.in[5], p.in[6], b, c * 64 + t, (isK ? 512 : 0) + hd * 128 + chl, isK ? 0.08838834764831845f : 1.f, a8);
;     uint4 o; o.x = pack2(a8[0], a8[1]); o.y = pack2(a8[2], a8[3]); o.z = pack2(a8[4], a8[5]); o.w = pack2(a8[6], a8[7]);
;     *(uint4*)((isK ? Ks : Qs) + t * 136 + chl) = o;
;   }
	v_lshlrev_b32_e32 v188, 16, v134
	v_and_b32_e32 v189, 0xffff0000, v134
	v_lshlrev_b32_e32 v190, 16, v135
	v_and_b32_e32 v191, 0xffff0000, v135
	v_lshlrev_b32_e32 v192, 16, v136
	v_and_b32_e32 v193, 0xffff0000, v136
	v_lshlrev_b32_e32 v194, 16, v137
	v_and_b32_e32 v195, 0xffff0000, v137
	v_fma_f32 v204, v94, v188, v4
	v_fma_f32 v205, v95, v189, v5
	v_fma_f32 v206, v96, v190, v6
	v_fma_f32 v207, v97, v191, v7
	v_fma_f32 v208, v98, v192, v0
	v_fma_f32 v209, v99, v193, v1
	v_fma_f32 v210, v100, v194, v2
	v_fma_f32 v211, v101, v195, v3
	v_lshlrev_b32_e32 v188, 16, v138
	v_and_b32_e32 v189, 0xffff0000, v138
	v_lshlrev_b32_e32 v190, 16, v139
	v_and_b32_e32 v191, 0xffff0000, v139
	v_lshlrev_b32_e32 v192, 16, v140
	v_and_b32_e32 v193, 0xffff0000, v140
	v_lshlrev_b32_e32 v194, 16, v141
	v_and_b32_e32 v195, 0xffff0000, v141
	v_fmac_f32_e32 v204, v102, v188
	v_fmac_f32_e32 v205, v103, v189
	v_fmac_f32_e32 v206, v104, v190
	v_fmac_f32_e32 v207, v105, v191
	v_fmac_f32_e32 v208, v106, v192
	v_fmac_f32_e32 v209, v107, v193
	v_fmac_f32_e32 v210, v108, v194
	v_fmac_f32_e32 v211, v109, v195
	v_lshlrev_b32_e32 v188, 16, v142
	v_and_b32_e32 v189, 0xffff0000, v142
	v_lshlrev_b32_e32 v190, 16, v143
	v_and_b32_e32 v191, 0xffff0000, v143
	v_lshlrev_b32_e32 v192, 16, v144
	v_and_b32_e32 v193, 0xffff0000, v144
	v_lshlrev_b32_e32 v194, 16, v145
	v_and_b32_e32 v195, 0xffff0000, v145
	v_fmac_f32_e32 v204, v110, v188
	v_fmac_f32_e32 v205, v111, v189
	v_fmac_f32_e32 v206, v112, v190
	v_fmac_f32_e32 v207, v113, v191
	v_fmac_f32_e32 v208, v114, v192
	v_fmac_f32_e32 v209, v115, v193
	v_fmac_f32_e32 v210, v116, v194
	v_fmac_f32_e32 v211, v117, v195
	v_lshlrev_b32_e32 v188, 16, v146
	v_and_b32_e32 v189, 0xffff0000, v146
	v_lshlrev_b32_e32 v190, 16, v147
	v_and_b32_e32 v191, 0xffff0000, v147
	v_lshlrev_b32_e32 v192, 16, v148
	v_and_b32_e32 v193, 0xffff0000, v148
	v_lshlrev_b32_e32 v194, 16, v149
	v_and_b32_e32 v195, 0xffff0000, v149
	v_fmac_f32_e32 v204, v8, v188
	v_fmac_f32_e32 v205, v9, v189
	v_fmac_f32_e32 v206, v10, v190
	v_fmac_f32_e32 v207, v11, v191
	v_fmac_f32_e32 v208, v12, v192
	v_fmac_f32_e32 v209, v13, v193
	v_fmac_f32_e32 v210, v14, v194
	v_fmac_f32_e32 v211, v15, v195
	v_mul_f32_e32 v212, 0xbfb8aa3b, v204
	v_mul_f32_e32 v213, 0xbfb8aa3b, v205
	v_mul_f32_e32 v214, 0xbfb8aa3b, v206
	v_mul_f32_e32 v215, 0xbfb8aa3b, v207
	v_mul_f32_e32 v216, 0xbfb8aa3b, v208
	v_mul_f32_e32 v217, 0xbfb8aa3b, v209
	v_mul_f32_e32 v218, 0xbfb8aa3b, v210
	v_mul_f32_e32 v219, 0xbfb8aa3b, v211
	v_mul_f32_e32 v188, v26, v204
	v_mul_f32_e32 v189, v27, v205
	v_mul_f32_e32 v190, v26, v206
	v_mul_f32_e32 v191, v27, v207
	v_mul_f32_e32 v192, v26, v208
	v_mul_f32_e32 v193, v27, v209
	v_mul_f32_e32 v194, v26, v210
	v_mul_f32_e32 v195, v27, v211
	v_exp_f32_e32 v212, v212
	v_exp_f32_e32 v213, v213
	v_exp_f32_e32 v214, v214
	v_exp_f32_e32 v215, v215
	v_exp_f32_e32 v216, v216
	v_exp_f32_e32 v217, v217
	v_exp_f32_e32 v218, v218
	v_exp_f32_e32 v219, v219
	v_add_f32_e32 v212, 1.0, v212
	v_add_f32_e32 v213, 1.0, v213
	v_add_f32_e32 v214, 1.0, v214
	v_add_f32_e32 v215, 1.0, v215
	v_add_f32_e32 v216, 1.0, v216
	v_add_f32_e32 v217, 1.0, v217
	v_add_f32_e32 v218, 1.0, v218
	v_add_f32_e32 v219, 1.0, v219
	v_rcp_f32_e32 v212, v212
	v_rcp_f32_e32 v213, v213
	v_rcp_f32_e32 v214, v214
	v_rcp_f32_e32 v215, v215
	v_rcp_f32_e32 v216, v216
	v_rcp_f32_e32 v217, v217
	v_rcp_f32_e32 v218, v218
	v_rcp_f32_e32 v219, v219
	v_mul_f32_e32 v188, v188, v212
	v_mul_f32_e32 v189, v189, v213
	v_mul_f32_e32 v190, v190, v214
	v_mul_f32_e32 v191, v191, v215
	v_mul_f32_e32 v192, v192, v216
	v_mul_f32_e32 v193, v193, v217
	v_mul_f32_e32 v194, v194, v218
	v_mul_f32_e32 v195, v195, v219
	v_cvt_pk_bf16_f32 v196, v188, v189
	v_cvt_pk_bf16_f32 v197, v190, v191
	v_cvt_pk_bf16_f32 v198, v192, v193
	v_cvt_pk_bf16_f32 v199, v194, v195
	ds_write_b128 v54, v[196:199] offset:2176
	v_add_u32_e32 v184, 40, v55
	v_add_u32_e32 v185, -1, v184
	v_mov_b32_e32 v134, 0
	v_mov_b32_e32 v135, 0
	v_mov_b32_e32 v136, 0
	v_mov_b32_e32 v137, 0
	v_mov_b32_e32 v138, 0
	v_mov_b32_e32 v139, 0
	v_mov_b32_e32 v140, 0
	v_mov_b32_e32 v141, 0
	v_mov_b32_e32 v142, 0
	v_mov_b32_e32 v143, 0
	v_mov_b32_e32 v144, 0
	v_mov_b32_e32 v145, 0
	v_mad_i64_i32 v[186:187], s[0:1], v185, s2, v[18:19]
	v_cmp_lt_u32_e64 s[0:1], 2, v184
	s_and_saveexec_b64 s[4:5], s[0:1]
	global_load_dwordx4 v[134:137], v[186:187], off offset:-4096
	s_or_b64 exec, exec, s[4:5]
	v_cmp_lt_u32_e64 s[0:1], 1, v184
	s_and_saveexec_b64 s[4:5], s[0:1]
	global_load_dwordx4 v[138:141], v[186:187], off offset:-2048
	s_or_b64 exec, exec, s[4:5]
	v_cmp_ne_u32_e64 s[0:1], 0, v184
	s_and_saveexec_b64 s[4:5], s[0:1]
	global_load_dwordx4 v[142:145], v[186:187], off
	s_or_b64 exec, exec, s[4:5]
	global_load_dwordx4 v[146:149], v[186:187], off offset:2048
	s_waitcnt vmcnt(12)
; DI unsigned pack2(float a, float b) { const f32x2 v = {a, b}; return __builtin_bit_cast(unsigned, __builtin_convertvector(v, bf16v2)); }
; DI void conv_unit(const u16* __restrict__ PM, const float* __restrict__ conv_w, const float* __restrict__ conv_b, int b, int sl0, int ch, float scale, float* a8) {
;   { const float4 b0 = *(const float4*)(conv_b + ch), b1 = *(const float4*)(conv_b + ch + 4); a8[0] = b0.x; a8[1] = b0.y; a8[2] = b0.z; a8[3] = b0.w; a8[4] = b1.x; a8[5] = b1.y; a8[6] = b1.z; a8[7] = b1.w; }
; #pragma unroll
;   for (int j = 0; j < 4; ++j) {
;     const int sl = sl0 - 3 + j;
;     if (sl >= 0) {
;       const uint4 raw = *(const uint4*)(PM + ((size_t)b * SEQ + sl) * 1024 + ch);
;       float x8[8]; unpack8(raw, x8);
;       const float4 w0 = *(const float4*)(conv_w + j * 1024 + ch), w1 = *(const float4*)(conv_w + j * 1024 + ch + 4);
;       a8[0] += w0.x * x8[0]; a8[1] += w0.y * x8[1]; a8[2] += w0.z * x8[2]; a8[3] += w0.w * x8[3];
;       a8[4] += w1.x * x8[4]; a8[5] += w1.y * x8[5]; a8[6] += w1.z * x8[6]; a8[7] += w1.w * x8[7];
;     }
;   }
; #pragma unroll
;   for (int e = 0; e < 8; ++e) { const float v = a8[e]; a8[e] = scale * v * __builtin_amdgcn_rcpf(1.f + __expf(-v)); }
; DI void mlstmC_pair(const Params& p, char* lds_all, int pair) {
;     ...
; #pragma unroll 1
;   for (int i = 0; i < 8; ++i) {
;     const int cg8 = ltid & 31, isK = cg8 >> 4, chl = (cg8 & 15) * 8, t = (ltid >> 5) + 8 * i;
;     float a8[8];
;     conv_unit(PM, p.in[5], p.in[6], b, c * 64 + t, (isK ? 512 : 0) + hd * 128 + chl, isK ? 0.08838834764831845f : 1.f, a8);
;     uint4 o; o.x = pack2(a8[0], a8[1]); o.y = pack2(a8[2], a8[3]); o.z = pack2(a8[4], a8[5]); o.w = pack2(a8[6], a8[7]);
;     *(uint4*)((isK ? Ks : Qs) + t * 136 + chl) = o;
;   }
	v_lshlrev_b32_e32 v188, 16, v150
	v_and_b32_e32 v189, 0xffff0000, v150
	v_lshlrev_b32_e32 v190, 16, v151
	v_and_b32_e32 v191, 0xffff0000, v151
	v_lshlrev_b32_e32 v192, 16, v152
	v_and_b32_e32 v193, 0xffff0000, v152
	v_lshlrev_b32_e32 v194, 16, v153
	v_and_b32_e32 v195, 0xffff0000, v153
	v_fma_f32 v204, v94, v188, v4
	v_fma_f32 v205, v95, v189, v5
	v_fma_f32 v206, v96, v190, v6
	v_fma_f32 v207, v97, v191, v7
	v_fma_f32 v208, v98, v192, v0
	v_fma_f32 v209, v99, v193, v1
	v_fma_f32 v210, v100, v194, v2
	v_fma_f32 v211, v101, v195, v3
	v_lshlrev_b32_e32 v188, 16, v154
	v_and_b32_e32 v189, 0xffff0000, v154
	v_lshlrev_b32_e32 v190, 16, v155
	v_and_b32_e32 v191, 0xffff0000, v155
	v_lshlrev_b32_e32 v192, 16, v156
	v_and_b32_e32 v193, 0xffff0000, v156
	v_lshlrev_b32_e32 v194, 16, v157
	v_and_b32_e32 v195, 0xffff0000, v157
	v_fmac_f32_e32 v204, v102, v188
	v_fmac_f32_e32 v205, v103, v189
	v_fmac_f32_e32 v206, v104, v190
	v_fmac_f32_e32 v207, v105, v191
	v_fmac_f32_e32 v208, v106, v192
	v_fmac_f32_e32 v209, v107, v193
	v_fmac_f32_e32 v210, v108, v194
	v_fmac_f32_e32 v211, v109, v195
	v_lshlrev_b32_e32 v188, 16, v158
	v_and_b32_e32 v189, 0xffff0000, v158
	v_lshlrev_b32_e32 v190, 16, v159
	v_and_b32_e32 v191, 0xffff0000, v159
	v_lshlrev_b32_e32 v192, 16, v160
	v_and_b32_e32 v193, 0xffff0000, v160
	v_lshlrev_b32_e32 v194, 16, v161
	v_and_b32_e32 v195, 0xffff0000, v161
	v_fmac_f32_e32 v204, v110, v188
	v_fmac_f32_e32 v205, v111, v189
	v_fmac_f32_e32 v206, v112, v190
	v_fmac_f32_e32 v207, v113, v191
	v_fmac_f32_e32 v208, v114, v192
	v_fmac_f32_e32 v209, v115, v193
	v_fmac_f32_e32 v210, v116, v194
	v_fmac_f32_e32 v211, v117, v195
	v_lshlrev_b32_e32 v188, 16, v162
	v_and_b32_e32 v189, 0xffff0000, v162
	v_lshlrev_b32_e32 v190, 16, v163
	v_and_b32_e32 v191, 0xffff0000, v163
	v_lshlrev_b32_e32 v192, 16, v164
	v_and_b32_e32 v193, 0xffff0000, v164
	v_lshlrev_b32_e32 v194, 16, v165
	v_and_b32_e32 v195, 0xffff0000, v165
	v_fmac_f32_e32 v204, v8, v188
	v_fmac_f32_e32 v205, v9, v189
	v_fmac_f32_e32 v206, v10, v190
	v_fmac_f32_e32 v207, v11, v191
	v_fmac_f32_e32 v208, v12, v192
	v_fmac_f32_e32 v209, v13, v193
	v_fmac_f32_e32 v210, v14, v194
	v_fmac_f32_e32 v211, v15, v195
	v_mul_f32_e32 v212, 0xbfb8aa3b, v204
	v_mul_f32_e32 v213, 0xbfb8aa3b, v205
	v_mul_f32_e32 v214, 0xbfb8aa3b, v206
	v_mul_f32_e32 v215, 0xbfb8aa3b, v207
	v_mul_f32_e32 v216, 0xbfb8aa3b, v208
	v_mul_f32_e32 v217, 0xbfb8aa3b, v209
	v_mul_f32_e32 v218, 0xbfb8aa3b, v210
	v_mul_f32_e32 v219, 0xbfb8aa3b, v211
	v_mul_f32_e32 v188, v26, v204
	v_mul_f32_e32 v189, v27, v205
	v_mul_f32_e32 v190, v26, v206
	v_mul_f32_e32 v191, v27, v207
	v_mul_f32_e32 v192, v26, v208
	v_mul_f32_e32 v193, v27, v209
	v_mul_f32_e32 v194, v26, v210
	v_mul_f32_e32 v195, v27, v211
	v_exp_f32_e32 v212, v212
	v_exp_f32_e32 v213, v213
	v_exp_f32_e32 v214, v214
	v_exp_f32_e32 v215, v215
	v_exp_f32_e32 v216, v216
	v_exp_f32_e32 v217, v217
	v_exp_f32_e32 v218, v218
	v_exp_f32_e32 v219, v219
	v_add_f32_e32 v212, 1.0, v212
	v_add_f32_e32 v213, 1.0, v213
	v_add_f32_e32 v214, 1.0, v214
	v_add_f32_e32 v215, 1.0, v215
	v_add_f32_e32 v216, 1.0, v216
	v_add_f32_e32 v217, 1.0, v217
	v_add_f32_e32 v218, 1.0, v218
	v_add_f32_e32 v219, 1.0, v219
	v_rcp_f32_e32 v212, v212
	v_rcp_f32_e32 v213, v213
	v_rcp_f32_e32 v214, v214
	v_rcp_f32_e32 v215, v215
	v_rcp_f32_e32 v216, v216
	v_rcp_f32_e32 v217, v217
	v_rcp_f32_e32 v218, v218
	v_rcp_f32_e32 v219, v219
	v_mul_f32_e32 v188, v188, v212
	v_mul_f32_e32 v189, v189, v213
	v_mul_f32_e32 v190, v190, v214
	v_mul_f32_e32 v191, v191, v215
	v_mul_f32_e32 v192, v192, v216
	v_mul_f32_e32 v193, v193, v217
	v_mul_f32_e32 v194, v194, v218
	v_mul_f32_e32 v195, v195, v219
	v_cvt_pk_bf16_f32 v196, v188, v189
	v_cvt_pk_bf16_f32 v197, v190, v191
	v_cvt_pk_bf16_f32 v198, v192, v193
	v_cvt_pk_bf16_f32 v199, v194, v195
	ds_write_b128 v54, v[196:199] offset:4352
	v_add_u32_e32 v184, 48, v55
	v_add_u32_e32 v185, -1, v184
	v_mov_b32_e32 v150, 0
	v_mov_b32_e32 v151, 0
	v_mov_b32_e32 v152, 0
	v_mov_b32_e32 v153, 0
	v_mov_b32_e32 v154, 0
	v_mov_b32_e32 v155, 0
	v_mov_b32_e32 v156, 0
	v_mov_b32_e32 v157, 0
	v_mov_b32_e32 v158, 0
	v_mov_b32_e32 v159, 0
	v_mov_b32_e32 v160, 0
	v_mov_b32_e32 v161, 0
	v_mad_i64_i32 v[186:187], s[0:1], v185, s2, v[18:19]
	v_cmp_lt_u32_e64 s[0:1], 2, v184
	s_and_saveexec_b64 s[4:5], s[0:1]
	global_load_dwordx4 v[150:153], v[186:187], off offset:-4096
	s_or_b64 exec, exec, s[4:5]
	v_cmp_lt_u32_e64 s[0:1], 1, v184
	s_and_saveexec_b64 s[4:5], s[0:1]
	global_load_dwordx4 v[154:157], v[186:187], off offset:-2048
	s_or_b64 exec, exec, s[4:5]
	v_cmp_ne_u32_e64 s[0:1], 0, v184
	s_and_saveexec_b64 s[4:5], s[0:1]
	global_load_dwordx4 v[158:161], v[186:187], off
	s_or_b64 exec, exec, s[4:5]
	global_load_dwordx4 v[162:165], v[186:187], off offset:2048
	s_waitcnt vmcnt(12)
; DI unsigned pack2(float a, float b) { const f32x2 v = {a, b}; return __builtin_bit_cast(unsigned, __builtin_convertvector(v, bf16v2)); }
; DI void conv_unit(const u16* __restrict__ PM, const float* __restrict__ conv_w, const float* __restrict__ conv_b, int b, int sl0, int ch, float scale, float* a8) {
;   { const float4 b0 = *(const float4*)(conv_b + ch), b1 = *(const float4*)(conv_b + ch + 4); a8[0] = b0.x; a8[1] = b0.y; a8[2] = b0.z; a8[3] = b0.w; a8[4] = b1.x; a8[5] = b1.y; a8[6] = b1.z; a8[7] = b1.w; }
; #pragma unroll
;   for (int j = 0; j < 4; ++j) {
;     const int sl = sl0 - 3 + j;
;     if (sl >= 0) {
;       const uint4 raw = *(const uint4*)(PM + ((size_t)b * SEQ + sl) * 1024 + ch);
;       float x8[8]; unpack8(raw, x8);
;       const float4 w0 = *(const float4*)(conv_w + j * 1024 + ch), w1 = *(const float4*)(conv_w + j * 1024 + ch + 4);
;       a8[0] += w0.x * x8[0]; a8[1] += w0.y * x8[1]; a8[2] += w0.z * x8[2]; a8[3] += w0.w * x8[3];
;       a8[4] += w1.x * x8[4]; a8[5] += w1.y * x8[5]; a8[6] += w1.z * x8[6]; a8[7] += w1.w * x8[7];
;     }
;   }
; #pragma unroll
;   for (int e = 0; e < 8; ++e) { const float v = a8[e]; a8[e] = scale * v * __builtin_amdgcn_rcpf(1.f + __expf(-v)); }
; DI void mlstmC_pair(const Params& p, char* lds_all, int pair) {
;     ...
; #pragma unroll 1
;   for (int i = 0; i < 8; ++i) {
;     const int cg8 = ltid & 31, isK = cg8 >> 4, chl = (cg8 & 15) * 8, t = (ltid >> 5) + 8 * i;
;     float a8[8];
;     conv_unit(PM, p.in[5], p.in[6], b, c * 64 + t, (isK ? 512 : 0) + hd * 128 + chl, isK ? 0.08838834764831845f : 1.f, a8);
;     uint4 o; o.x = pack2(a8[0], a8[1]); o.y = pack2(a8[2], a8[3]); o.z = pack2(a8[4], a8[5]); o.w = pack2(a8[6], a8[7]);
;     *(uint4*)((isK ? Ks : Qs) + t * 136 + chl) = o;
;   }
	v_lshlrev_b32_e32 v188, 16, v166
	v_and_b32_e32 v189, 0xffff0000, v166
	v_lshlrev_b32_e32 v190, 16, v167
	v_and_b32_e32 v191, 0xffff0000, v167
	v_lshlrev_b32_e32 v192, 16, v168
	v_and_b32_e32 v193, 0xffff0000, v168
	v_lshlrev_b32_e32 v194, 16, v169
	v_and_b32_e32 v195, 0xffff0000, v169
	v_fma_f32 v204, v94, v188, v4
	v_fma_f32 v205, v95, v189, v5
	v_fma_f32 v206, v96, v190, v6
	v_fma_f32 v207, v97, v191, v7
	v_fma_f32 v208, v98, v192, v0
	v_fma_f32 v209, v99, v193, v1
	v_fma_f32 v210, v100, v194, v2
	v_fma_f32 v211, v101, v195, v3
	v_lshlrev_b32_e32 v188, 16, v170
	v_and_b32_e32 v189, 0xffff0000, v170
	v_lshlrev_b32_e32 v190, 16, v171
	v_and_b32_e32 v191, 0xffff0000, v171
	v_lshlrev_b32_e32 v192, 16, v172
	v_and_b32_e32 v193, 0xffff0000, v172
	v_lshlrev_b32_e32 v194, 16, v173
	v_and_b32_e32 v195, 0xffff0000, v173
	v_fmac_f32_e32 v204, v102, v188
	v_fmac_f32_e32 v205, v103, v189
	v_fmac_f32_e32 v206, v104, v190
	v_fmac_f32_e32 v207, v105, v191
	v_fmac_f32_e32 v208, v106, v192
	v_fmac_f32_e32 v209, v107, v193
	v_fmac_f32_e32 v210, v108, v194
	v_fmac_f32_e32 v211, v109, v195
	v_lshlrev_b32_e32 v188, 16, v174
	v_and_b32_e32 v189, 0xffff0000, v174
	v_lshlrev_b32_e32 v190, 16, v175
	v_and_b32_e32 v191, 0xffff0000, v175
	v_lshlrev_b32_e32 v192, 16, v176
	v_and_b32_e32 v193, 0xffff0000, v176
	v_lshlrev_b32_e32 v194, 16, v177
	v_and_b32_e32 v195, 0xffff0000, v177
	v_fmac_f32_e32 v204, v110, v188
	v_fmac_f32_e32 v205, v111, v189
	v_fmac_f32_e32 v206, v112, v190
	v_fmac_f32_e32 v207, v113, v191
	v_fmac_f32_e32 v208, v114, v192
	v_fmac_f32_e32 v209, v115, v193
	v_fmac_f32_e32 v210, v116, v194
	v_fmac_f32_e32 v211, v117, v195
	v_lshlrev_b32_e32 v188, 16, v178
	v_and_b32_e32 v189, 0xffff0000, v178
	v_lshlrev_b32_e32 v190, 16, v179
	v_and_b32_e32 v191, 0xffff0000, v179
	v_lshlrev_b32_e32 v192, 16, v180
	v_and_b32_e32 v193, 0xffff0000, v180
	v_lshlrev_b32_e32 v194, 16, v181
	v_and_b32_e32 v195, 0xffff0000, v181
	v_fmac_f32_e32 v204, v8, v188
	v_fmac_f32_e32 v205, v9, v189
	v_fmac_f32_e32 v206, v10, v190
	v_fmac_f32_e32 v207, v11, v191
	v_fmac_f32_e32 v208, v12, v192
	v_fmac_f32_e32 v209, v13, v193
	v_fmac_f32_e32 v210, v14, v194
	v_fmac_f32_e32 v211, v15, v195
	v_mul_f32_e32 v212, 0xbfb8aa3b, v204
	v_mul_f32_e32 v213, 0xbfb8aa3b, v205
	v_mul_f32_e32 v214, 0xbfb8aa3b, v206
	v_mul_f32_e32 v215, 0xbfb8aa3b, v207
	v_mul_f32_e32 v216, 0xbfb8aa3b, v208
	v_mul_f32_e32 v217, 0xbfb8aa3b, v209
	v_mul_f32_e32 v218, 0xbfb8aa3b, v210
	v_mul_f32_e32 v219, 0xbfb8aa3b, v211
	v_mul_f32_e32 v188, v26, v204
	v_mul_f32_e32 v189, v27, v205
	v_mul_f32_e32 v190, v26, v206
	v_mul_f32_e32 v191, v27, v207
	v_mul_f32_e32 v192, v26, v208
	v_mul_f32_e32 v193, v27, v209
	v_mul_f32_e32 v194, v26, v210
	v_mul_f32_e32 v195, v27, v211
	v_exp_f32_e32 v212, v212
	v_exp_f32_e32 v213, v213
	v_exp_f32_e32 v214, v214
	v_exp_f32_e32 v215, v215
	v_exp_f32_e32 v216, v216
	v_exp_f32_e32 v217, v217
	v_exp_f32_e32 v218, v218
	v_exp_f32_e32 v219, v219
	v_add_f32_e32 v212, 1.0, v212
	v_add_f32_e32 v213, 1.0, v213
	v_add_f32_e32 v214, 1.0, v214
	v_add_f32_e32 v215, 1.0, v215
	v_add_f32_e32 v216, 1.0, v216
	v_add_f32_e32 v217, 1.0, v217
	v_add_f32_e32 v218, 1.0, v218
	v_add_f32_e32 v219, 1.0, v219
	v_rcp_f32_e32 v212, v212
	v_rcp_f32_e32 v213, v213
	v_rcp_f32_e32 v214, v214
	v_rcp_f32_e32 v215, v215
	v_rcp_f32_e32 v216, v216
	v_rcp_f32_e32 v217, v217
	v_rcp_f32_e32 v218, v218
	v_rcp_f32_e32 v219, v219
	v_mul_f32_e32 v188, v188, v212
	v_mul_f32_e32 v189, v189, v213
	v_mul_f32_e32 v190, v190, v214
	v_mul_f32_e32 v191, v191, v215
	v_mul_f32_e32 v192, v192, v216
	v_mul_f32_e32 v193, v193, v217
	v_mul_f32_e32 v194, v194, v218
	v_mul_f32_e32 v195, v195, v219
	v_cvt_pk_bf16_f32 v196, v188, v189
	v_cvt_pk_bf16_f32 v197, v190, v191
	v_cvt_pk_bf16_f32 v198, v192, v193
	v_cvt_pk_bf16_f32 v199, v194, v195
	ds_write_b128 v54, v[196:199] offset:6528
	v_add_u32_e32 v184, 56, v55
	v_add_u32_e32 v185, -1, v184
	v_mov_b32_e32 v166, 0
	v_mov_b32_e32 v167, 0
	v_mov_b32_e32 v168, 0
	v_mov_b32_e32 v169, 0
	v_mov_b32_e32 v170, 0
	v_mov_b32_e32 v171, 0
	v_mov_b32_e32 v172, 0
	v_mov_b32_e32 v173, 0
	v_mov_b32_e32 v174, 0
	v_mov_b32_e32 v175, 0
	v_mov_b32_e32 v176, 0
	v_mov_b32_e32 v177, 0
	v_mad_i64_i32 v[186:187], s[0:1], v185, s2, v[18:19]
	v_cmp_lt_u32_e64 s[0:1], 2, v184
	s_and_saveexec_b64 s[4:5], s[0:1]
	global_load_dwordx4 v[166:169], v[186:187], off offset:-4096
	s_or_b64 exec, exec, s[4:5]
	v_cmp_lt_u32_e64 s[0:1], 1, v184
	s_and_saveexec_b64 s[4:5], s[0:1]
	global_load_dwordx4 v[170:173], v[186:187], off offset:-2048
	s_or_b64 exec, exec, s[4:5]
	v_cmp_ne_u32_e64 s[0:1], 0, v184
	s_and_saveexec_b64 s[4:5], s[0:1]
	global_load_dwordx4 v[174:177], v[186:187], off
	s_or_b64 exec, exec, s[4:5]
	global_load_dwordx4 v[178:181], v[186:187], off offset:2048
	s_waitcnt vmcnt(12)
; DI unsigned pack2(float a, float b) { const f32x2 v = {a, b}; return __builtin_bit_cast(unsigned, __builtin_convertvector(v, bf16v2)); }
; DI void conv_unit(const u16* __restrict__ PM, const float* __restrict__ conv_w, const float* __restrict__ conv_b, int b, int sl0, int ch, float scale, float* a8) {
;   { const float4 b0 = *(const float4*)(conv_b + ch), b1 = *(const float4*)(conv_b + ch + 4); a8[0] = b0.x; a8[1] = b0.y; a8[2] = b0.z; a8[3] = b0.w; a8[4] = b1.x; a8[5] = b1.y; a8[6] = b1.z; a8[7] = b1.w; }
; #pragma unroll
;   for (int j = 0; j < 4; ++j) {
;     const int sl = sl0 - 3 + j;
;     if (sl >= 0) {
;       const uint4 raw = *(const uint4*)(PM + ((size_t)b * SEQ + sl) * 1024 + ch);
;       float x8[8]; unpack8(raw, x8);
;       const float4 w0 = *(const float4*)(conv_w + j * 1024 + ch), w1 = *(const float4*)(conv_w + j * 1024 + ch + 4);
;       a8[0] += w0.x * x8[0]; a8[1] += w0.y * x8[1]; a8[2] += w0.z * x8[2]; a8[3] += w0.w * x8[3];
;       a8[4] += w1.x * x8[4]; a8[5] += w1.y * x8[5]; a8[6] += w1.z * x8[6]; a8[7] += w1.w * x8[7];
;     }
;   }
; #pragma unroll
;   for (int e = 0; e < 8; ++e) { const float v = a8[e]; a8[e] = scale * v * __builtin_amdgcn_rcpf(1.f + __expf(-v)); }
; DI void mlstmC_pair(const Params& p, char* lds_all, int pair) {
;     ...
; #pragma unroll 1
;   for (int i = 0; i < 8; ++i) {
;     const int cg8 = ltid & 31, isK = cg8 >> 4, chl = (cg8 & 15) * 8, t = (ltid >> 5) + 8 * i;
;     float a8[8];
;     conv_unit(PM, p.in[5], p.in[6], b, c * 64 + t, (isK ? 512 : 0) + hd * 128 + chl, isK ? 0.08838834764831845f : 1.f, a8);
;     uint4 o; o.x = pack2(a8[0], a8[1]); o.y = pack2(a8[2], a8[3]); o.z = pack2(a8[4], a8[5]); o.w = pack2(a8[6], a8[7]);
;     *(uint4*)((isK ? Ks : Qs) + t * 136 + chl) = o;
;   }
	v_lshlrev_b32_e32 v188, 16, v118
	v_and_b32_e32 v189, 0xffff0000, v118
	v_lshlrev_b32_e32 v190, 16, v119
	v_and_b32_e32 v191, 0xffff0000, v119
	v_lshlrev_b32_e32 v192, 16, v120
	v_and_b32_e32 v193, 0xffff0000, v120
	v_lshlrev_b32_e32 v194, 16, v121
	v_and_b32_e32 v195, 0xffff0000, v121
	v_fma_f32 v204, v94, v188, v4
	v_fma_f32 v205, v95, v189, v5
	v_fma_f32 v206, v96, v190, v6
	v_fma_f32 v207, v97, v191, v7
	v_fma_f32 v208, v98, v192, v0
	v_fma_f32 v209, v99, v193, v1
	v_fma_f32 v210, v100, v194, v2
	v_fma_f32 v211, v101, v195, v3
	v_lshlrev_b32_e32 v188, 16, v122
	v_and_b32_e32 v189, 0xffff0000, v122
	v_lshlrev_b32_e32 v190, 16, v123
	v_and_b32_e32 v191, 0xffff0000, v123
	v_lshlrev_b32_e32 v192, 16, v124
	v_and_b32_e32 v193, 0xffff0000, v124
	v_lshlrev_b32_e32 v194, 16, v125
	v_and_b32_e32 v195, 0xffff0000, v125
	v_fmac_f32_e32 v204, v102, v188
	v_fmac_f32_e32 v205, v103, v189
	v_fmac_f32_e32 v206, v104, v190
	v_fmac_f32_e32 v207, v105, v191
	v_fmac_f32_e32 v208, v106, v192
	v_fmac_f32_e32 v209, v107, v193
	v_fmac_f32_e32 v210, v108, v194
	v_fmac_f32_e32 v211, v109, v195
	v_lshlrev_b32_e32 v188, 16, v126
	v_and_b32_e32 v189, 0xffff0000, v126
	v_lshlrev_b32_e32 v190, 16, v127
	v_and_b32_e32 v191, 0xffff0000, v127
	v_lshlrev_b32_e32 v192, 16, v128
	v_and_b32_e32 v193, 0xffff0000, v128
	v_lshlrev_b32_e32 v194, 16, v129
	v_and_b32_e32 v195, 0xffff0000, v129
	v_fmac_f32_e32 v204, v110, v188
	v_fmac_f32_e32 v205, v111, v189
	v_fmac_f32_e32 v206, v112, v190
	v_fmac_f32_e32 v207, v113, v191
	v_fmac_f32_e32 v208, v114, v192
	v_fmac_f32_e32 v209, v115, v193
	v_fmac_f32_e32 v210, v116, v194
	v_fmac_f32_e32 v211, v117, v195
	v_lshlrev_b32_e32 v188, 16, v130
	v_and_b32_e32 v189, 0xffff0000, v130
	v_lshlrev_b32_e32 v190, 16, v131
	v_and_b32_e32 v191, 0xffff0000, v131
	v_lshlrev_b32_e32 v192, 16, v132
	v_and_b32_e32 v193, 0xffff0000, v132
	v_lshlrev_b32_e32 v194, 16, v133
	v_and_b32_e32 v195, 0xffff0000, v133
	v_fmac_f32_e32 v204, v8, v188
	v_fmac_f32_e32 v205, v9, v189
	v_fmac_f32_e32 v206, v10, v190
	v_fmac_f32_e32 v207, v11, v191
	v_fmac_f32_e32 v208, v12, v192
	v_fmac_f32_e32 v209, v13, v193
	v_fmac_f32_e32 v210, v14, v194
	v_fmac_f32_e32 v211, v15, v195
	v_mul_f32_e32 v212, 0xbfb8aa3b, v204
	v_mul_f32_e32 v213, 0xbfb8aa3b, v205
	v_mul_f32_e32 v214, 0xbfb8aa3b, v206
	v_mul_f32_e32 v215, 0xbfb8aa3b, v207
	v_mul_f32_e32 v216, 0xbfb8aa3b, v208
	v_mul_f32_e32 v217, 0xbfb8aa3b, v209
	v_mul_f32_e32 v218, 0xbfb8aa3b, v210
	v_mul_f32_e32 v219, 0xbfb8aa3b, v211
	v_mul_f32_e32 v188, v26, v204
	v_mul_f32_e32 v189, v27, v205
	v_mul_f32_e32 v190, v26, v206
	v_mul_f32_e32 v191, v27, v207
	v_mul_f32_e32 v192, v26, v208
	v_mul_f32_e32 v193, v27, v209
	v_mul_f32_e32 v194, v26, v210
	v_mul_f32_e32 v195, v27, v211
	v_exp_f32_e32 v212, v212
	v_exp_f32_e32 v213, v213
	v_exp_f32_e32 v214, v214
	v_exp_f32_e32 v215, v215
	v_exp_f32_e32 v216, v216
	v_exp_f32_e32 v217, v217
	v_exp_f32_e32 v218, v218
	v_exp_f32_e32 v219, v219
	v_add_f32_e32 v212, 1.0, v212
	v_add_f32_e32 v213, 1.0, v213
	v_add_f32_e32 v214, 1.0, v214
	v_add_f32_e32 v215, 1.0, v215
	v_add_f32_e32 v216, 1.0, v216
	v_add_f32_e32 v217, 1.0, v217
	v_add_f32_e32 v218, 1.0, v218
	v_add_f32_e32 v219, 1.0, v219
	v_rcp_f32_e32 v212, v212
	v_rcp_f32_e32 v213, v213
	v_rcp_f32_e32 v214, v214
	v_rcp_f32_e32 v215, v215
	v_rcp_f32_e32 v216, v216
	v_rcp_f32_e32 v217, v217
	v_rcp_f32_e32 v218, v218
	v_rcp_f32_e32 v219, v219
	v_mul_f32_e32 v188, v188, v212
	v_mul_f32_e32 v189, v189, v213
	v_mul_f32_e32 v190, v190, v214
	v_mul_f32_e32 v191, v191, v215
	v_mul_f32_e32 v192, v192, v216
	v_mul_f32_e32 v193, v193, v217
	v_mul_f32_e32 v194, v194, v218
	v_mul_f32_e32 v195, v195, v219
	v_cvt_pk_bf16_f32 v196, v188, v189
	v_cvt_pk_bf16_f32 v197, v190, v191
	v_cvt_pk_bf16_f32 v198, v192, v193
	v_cvt_pk_bf16_f32 v199, v194, v195
	ds_write_b128 v54, v[196:199] offset:8704
	s_waitcnt vmcnt(8)
	v_lshlrev_b32_e32 v188, 16, v134
	v_and_b32_e32 v189, 0xffff0000, v134
	v_lshlrev_b32_e32 v190, 16, v135
	v_and_b32_e32 v191, 0xffff0000, v135
	v_lshlrev_b32_e32 v192, 16, v136
	v_and_b32_e32 v193, 0xffff0000, v136
	v_lshlrev_b32_e32 v194, 16, v137
	v_and_b32_e32 v195, 0xffff0000, v137
	v_fma_f32 v204, v94, v188, v4
	v_fma_f32 v205, v95, v189, v5
	v_fma_f32 v206, v96, v190, v6
	v_fma_f32 v207, v97, v191, v7
	v_fma_f32 v208, v98, v192, v0
	v_fma_f32 v209, v99, v193, v1
	v_fma_f32 v210, v100, v194, v2
	v_fma_f32 v211, v101, v195, v3
	v_lshlrev_b32_e32 v188, 16, v138
	v_and_b32_e32 v189, 0xffff0000, v138
	v_lshlrev_b32_e32 v190, 16, v139
	v_and_b32_e32 v191, 0xffff0000, v139
	v_lshlrev_b32_e32 v192, 16, v140
	v_and_b32_e32 v193, 0xffff0000, v140
	v_lshlrev_b32_e32 v194, 16, v141
	v_and_b32_e32 v195, 0xffff0000, v141
	v_fmac_f32_e32 v204, v102, v188
	v_fmac_f32_e32 v205, v103, v189
	v_fmac_f32_e32 v206, v104, v190
	v_fmac_f32_e32 v207, v105, v191
	v_fmac_f32_e32 v208, v106, v192
	v_fmac_f32_e32 v209, v107, v193
	v_fmac_f32_e32 v210, v108, v194
	v_fmac_f32_e32 v211, v109, v195
	v_lshlrev_b32_e32 v188, 16, v142
	v_and_b32_e32 v189, 0xffff0000, v142
	v_lshlrev_b32_e32 v190, 16, v143
	v_and_b32_e32 v191, 0xffff0000, v143
	v_lshlrev_b32_e32 v192, 16, v144
	v_and_b32_e32 v193, 0xffff0000, v144
	v_lshlrev_b32_e32 v194, 16, v145
	v_and_b32_e32 v195, 0xffff0000, v145
	v_fmac_f32_e32 v204, v110, v188
	v_fmac_f32_e32 v205, v111, v189
	v_fmac_f32_e32 v206, v112, v190
	v_fmac_f32_e32 v207, v113, v191
	v_fmac_f32_e32 v208, v114, v192
	v_fmac_f32_e32 v209, v115, v193
	v_fmac_f32_e32 v210, v116, v194
	v_fmac_f32_e32 v211, v117, v195
	v_lshlrev_b32_e32 v188, 16, v146
	v_and_b32_e32 v189, 0xffff0000, v146
	v_lshlrev_b32_e32 v190, 16, v147
	v_and_b32_e32 v191, 0xffff0000, v147
; DI unsigned pack2(float a, float b) { const f32x2 v = {a, b}; return __builtin_bit_cast(unsigned, __builtin_convertvector(v, bf16v2)); }
; DI void conv_unit(const u16* __restrict__ PM, const float* __restrict__ conv_w, const float* __restrict__ conv_b, int b, int sl0, int ch, float scale, float* a8) {
;     ...
;   for (int j = 0; j < 4; ++j) {
;     const int sl = sl0 - 3 + j;
;     if (sl >= 0) {
;       const uint4 raw = *(const uint4*)(PM + ((size_t)b * SEQ + sl) * 1024 + ch);
;       float x8[8]; unpack8(raw, x8);
;       const float4 w0 = *(const float4*)(conv_w + j * 1024 + ch), w1 = *(const float4*)(conv_w + j * 1024 + ch + 4);
;       a8[0] += w0.x * x8[0]; a8[1] += w0.y * x8[1]; a8[2] += w0.z * x8[2]; a8[3] += w0.w * x8[3];
;       a8[4] += w1.x * x8[4]; a8[5] += w1.y * x8[5]; a8[6] += w1.z * x8[6]; a8[7] += w1.w * x8[7];
;     }
;   }
; #pragma unroll
;   for (int e = 0; e < 8; ++e) { const float v = a8[e]; a8[e] = scale * v * __builtin_amdgcn_rcpf(1.f + __expf(-v)); }
; DI void mlstmC_pair(const Params& p, char* lds_all, int pair) {
;     ...
;   for (int i = 0; i < 8; ++i) {
;     const int cg8 = ltid & 31, isK = cg8 >> 4, chl = (cg8 & 15) * 8, t = (ltid >> 5) + 8 * i;
;     float a8[8];
;     conv_unit(PM, p.in[5], p.in[6], b, c * 64 + t, (isK ? 512 : 0) + hd * 128 + chl, isK ? 0.08838834764831845f : 1.f, a8);
;     uint4 o; o.x = pack2(a8[0], a8[1]); o.y = pack2(a8[2], a8[3]); o.z = pack2(a8[4], a8[5]); o.w = pack2(a8[6], a8[7]);
;     *(uint4*)((isK ? Ks : Qs) + t * 136 + chl) = o;
	v_lshlrev_b32_e32 v192, 16, v148
	v_and_b32_e32 v193, 0xffff0000, v148
	v_lshlrev_b32_e32 v194, 16, v149
	v_and_b32_e32 v195, 0xffff0000, v149
	v_fmac_f32_e32 v204, v8, v188
	v_fmac_f32_e32 v205, v9, v189
	v_fmac_f32_e32 v206, v10, v190
	v_fmac_f32_e32 v207, v11, v191
	v_fmac_f32_e32 v208, v12, v192
	v_fmac_f32_e32 v209, v13, v193
	v_fmac_f32_e32 v210, v14, v194
	v_fmac_f32_e32 v211, v15, v195
	v_mul_f32_e32 v212, 0xbfb8aa3b, v204
	v_mul_f32_e32 v213, 0xbfb8aa3b, v205
	v_mul_f32_e32 v214, 0xbfb8aa3b, v206
	v_mul_f32_e32 v215, 0xbfb8aa3b, v207
	v_mul_f32_e32 v216, 0xbfb8aa3b, v208
	v_mul_f32_e32 v217, 0xbfb8aa3b, v209
	v_mul_f32_e32 v218, 0xbfb8aa3b, v210
	v_mul_f32_e32 v219, 0xbfb8aa3b, v211
	v_mul_f32_e32 v188, v26, v204
	v_mul_f32_e32 v189, v27, v205
	v_mul_f32_e32 v190, v26, v206
	v_mul_f32_e32 v191, v27, v207
	v_mul_f32_e32 v192, v26, v208
	v_mul_f32_e32 v193, v27, v209
	v_mul_f32_e32 v194, v26, v210
	v_mul_f32_e32 v195, v27, v211
	v_exp_f32_e32 v212, v212
	v_exp_f32_e32 v213, v213
	v_exp_f32_e32 v214, v214
	v_exp_f32_e32 v215, v215
	v_exp_f32_e32 v216, v216
	v_exp_f32_e32 v217, v217
	v_exp_f32_e32 v218, v218
	v_exp_f32_e32 v219, v219
	v_add_f32_e32 v212, 1.0, v212
	v_add_f32_e32 v213, 1.0, v213
	v_add_f32_e32 v214, 1.0, v214
	v_add_f32_e32 v215, 1.0, v215
	v_add_f32_e32 v216, 1.0, v216
	v_add_f32_e32 v217, 1.0, v217
	v_add_f32_e32 v218, 1.0, v218
	v_add_f32_e32 v219, 1.0, v219
	v_rcp_f32_e32 v212, v212
	v_rcp_f32_e32 v213, v213
	v_rcp_f32_e32 v214, v214
	v_rcp_f32_e32 v215, v215
	v_rcp_f32_e32 v216, v216
	v_rcp_f32_e32 v217, v217
	v_rcp_f32_e32 v218, v218
	v_rcp_f32_e32 v219, v219
	v_mul_f32_e32 v188, v188, v212
	v_mul_f32_e32 v189, v189, v213
	v_mul_f32_e32 v190, v190, v214
	v_mul_f32_e32 v191, v191, v215
	v_mul_f32_e32 v192, v192, v216
	v_mul_f32_e32 v193, v193, v217
	v_mul_f32_e32 v194, v194, v218
	v_mul_f32_e32 v195, v195, v219
	v_cvt_pk_bf16_f32 v196, v188, v189
	v_cvt_pk_bf16_f32 v197, v190, v191
	v_cvt_pk_bf16_f32 v198, v192, v193
	v_cvt_pk_bf16_f32 v199, v194, v195
	ds_write_b128 v54, v[196:199] offset:10880
	s_waitcnt vmcnt(4)
	v_lshlrev_b32_e32 v188, 16, v150
	v_and_b32_e32 v189, 0xffff0000, v150
	v_lshlrev_b32_e32 v190, 16, v151
	v_and_b32_e32 v191, 0xffff0000, v151
	v_lshlrev_b32_e32 v192, 16, v152
	v_and_b32_e32 v193, 0xffff0000, v152
	v_lshlrev_b32_e32 v194, 16, v153
	v_and_b32_e32 v195, 0xffff0000, v153
	v_fma_f32 v204, v94, v188, v4
	v_fma_f32 v205, v95, v189, v5
	v_fma_f32 v206, v96, v190, v6
	v_fma_f32 v207, v97, v191, v7
	v_fma_f32 v208, v98, v192, v0
	v_fma_f32 v209, v99, v193, v1
	v_fma_f32 v210, v100, v194, v2
	v_fma_f32 v211, v101, v195, v3
	v_lshlrev_b32_e32 v188, 16, v154
	v_and_b32_e32 v189, 0xffff0000, v154
	v_lshlrev_b32_e32 v190, 16, v155
	v_and_b32_e32 v191, 0xffff0000, v155
	v_lshlrev_b32_e32 v192, 16, v156
	v_and_b32_e32 v193, 0xffff0000, v156
	v_lshlrev_b32_e32 v194, 16, v157
	v_and_b32_e32 v195, 0xffff0000, v157
	v_fmac_f32_e32 v204, v102, v188
	v_fmac_f32_e32 v205, v103, v189
	v_fmac_f32_e32 v206, v104, v190
	v_fmac_f32_e32 v207, v105, v191
	v_fmac_f32_e32 v208, v106, v192
	v_fmac_f32_e32 v209, v107, v193
	v_fmac_f32_e32 v210, v108, v194
	v_fmac_f32_e32 v211, v109, v195
	v_lshlrev_b32_e32 v188, 16, v158
	v_and_b32_e32 v189, 0xffff0000, v158
	v_lshlrev_b32_e32 v190, 16, v159
	v_and_b32_e32 v191, 0xffff0000, v159
	v_lshlrev_b32_e32 v192, 16, v160
	v_and_b32_e32 v193, 0xffff0000, v160
	v_lshlrev_b32_e32 v194, 16, v161
	v_and_b32_e32 v195, 0xffff0000, v161
	v_fmac_f32_e32 v204, v110, v188
	v_fmac_f32_e32 v205, v111, v189
	v_fmac_f32_e32 v206, v112, v190
	v_fmac_f32_e32 v207, v113, v191
	v_fmac_f32_e32 v208, v114, v192
	v_fmac_f32_e32 v209, v115, v193
	v_fmac_f32_e32 v210, v116, v194
	v_fmac_f32_e32 v211, v117, v195
	v_lshlrev_b32_e32 v188, 16, v162
	v_and_b32_e32 v189, 0xffff0000, v162
	v_lshlrev_b32_e32 v190, 16, v163
	v_and_b32_e32 v191, 0xffff0000, v163
	v_lshlrev_b32_e32 v192, 16, v164
	v_and_b32_e32 v193, 0xffff0000, v164
	v_lshlrev_b32_e32 v194, 16, v165
	v_and_b32_e32 v195, 0xffff0000, v165
	v_fmac_f32_e32 v204, v8, v188
	v_fmac_f32_e32 v205, v9, v189
	v_fmac_f32_e32 v206, v10, v190
	v_fmac_f32_e32 v207, v11, v191
	v_fmac_f32_e32 v208, v12, v192
	v_fmac_f32_e32 v209, v13, v193
	v_fmac_f32_e32 v210, v14, v194
	v_fmac_f32_e32 v211, v15, v195
	v_mul_f32_e32 v212, 0xbfb8aa3b, v204
	v_mul_f32_e32 v213, 0xbfb8aa3b, v205
	v_mul_f32_e32 v214, 0xbfb8aa3b, v206
	v_mul_f32_e32 v215, 0xbfb8aa3b, v207
	v_mul_f32_e32 v216, 0xbfb8aa3b, v208
	v_mul_f32_e32 v217, 0xbfb8aa3b, v209
	v_mul_f32_e32 v218, 0xbfb8aa3b, v210
	v_mul_f32_e32 v219, 0xbfb8aa3b, v211
	v_mul_f32_e32 v188, v26, v204
	v_mul_f32_e32 v189, v27, v205
	v_mul_f32_e32 v190, v26, v206
	v_mul_f32_e32 v191, v27, v207
	v_mul_f32_e32 v192, v26, v208
	v_mul_f32_e32 v193, v27, v209
	v_mul_f32_e32 v194, v26, v210
	v_mul_f32_e32 v195, v27, v211
	v_exp_f32_e32 v212, v212
	v_exp_f32_e32 v213, v213
	v_exp_f32_e32 v214, v214
	v_exp_f32_e32 v215, v215
	v_exp_f32_e32 v216, v216
	v_exp_f32_e32 v217, v217
	v_exp_f32_e32 v218, v218
	v_exp_f32_e32 v219, v219
	v_add_f32_e32 v212, 1.0, v212
	v_add_f32_e32 v213, 1.0, v213
	v_add_f32_e32 v214, 1.0, v214
	v_add_f32_e32 v215, 1.0, v215
	v_add_f32_e32 v216, 1.0, v216
	v_add_f32_e32 v217, 1.0, v217
	v_add_f32_e32 v218, 1.0, v218
	v_add_f32_e32 v219, 1.0, v219
	v_rcp_f32_e32 v212, v212
	v_rcp_f32_e32 v213, v213
	v_rcp_f32_e32 v214, v214
	v_rcp_f32_e32 v215, v215
	v_rcp_f32_e32 v216, v216
	v_rcp_f32_e32 v217, v217
	v_rcp_f32_e32 v218, v218
	v_rcp_f32_e32 v219, v219
	v_mul_f32_e32 v188, v188, v212
	v_mul_f32_e32 v189, v189, v213
	v_mul_f32_e32 v190, v190, v214
	v_mul_f32_e32 v191, v191, v215
	v_mul_f32_e32 v192, v192, v216
	v_mul_f32_e32 v193, v193, v217
	v_mul_f32_e32 v194, v194, v218
	v_mul_f32_e32 v195, v195, v219
	v_cvt_pk_bf16_f32 v196, v188, v189
	v_cvt_pk_bf16_f32 v197, v190, v191
	v_cvt_pk_bf16_f32 v198, v192, v193
	v_cvt_pk_bf16_f32 v199, v194, v195
	ds_write_b128 v54, v[196:199] offset:13056
	s_waitcnt vmcnt(0)
; DI unsigned pack2(float a, float b) { const f32x2 v = {a, b}; return __builtin_bit_cast(unsigned, __builtin_convertvector(v, bf16v2)); }
; DI void conv_unit(const u16* __restrict__ PM, const float* __restrict__ conv_w, const float* __restrict__ conv_b, int b, int sl0, int ch, float scale, float* a8) {
;     ...
;   for (int j = 0; j < 4; ++j) {
;     const int sl = sl0 - 3 + j;
;     if (sl >= 0) {
;       const uint4 raw = *(const uint4*)(PM + ((size_t)b * SEQ + sl) * 1024 + ch);
;       float x8[8]; unpack8(raw, x8);
;       const float4 w0 = *(const float4*)(conv_w + j * 1024 + ch), w1 = *(const float4*)(conv_w + j * 1024 + ch + 4);
;       a8[0] += w0.x * x8[0]; a8[1] += w0.y * x8[1]; a8[2] += w0.z * x8[2]; a8[3] += w0.w * x8[3];
;       a8[4] += w1.x * x8[4]; a8[5] += w1.y * x8[5]; a8[6] += w1.z * x8[6]; a8[7] += w1.w * x8[7];
;     }
;   }
; #pragma unroll
;   for (int e = 0; e < 8; ++e) { const float v = a8[e]; a8[e] = scale * v * __builtin_amdgcn_rcpf(1.f + __expf(-v)); }
; DI void mlstmC_pair(const Params& p, char* lds_all, int pair) {
;     ...
;   for (int i = 0; i < 8; ++i) {
;     const int cg8 = ltid & 31, isK = cg8 >> 4, chl = (cg8 & 15) * 8, t = (ltid >> 5) + 8 * i;
;     float a8[8];
;     conv_unit(PM, p.in[5], p.in[6], b, c * 64 + t, (isK ? 512 : 0) + hd * 128 + chl, isK ? 0.08838834764831845f : 1.f, a8);
;     uint4 o; o.x = pack2(a8[0], a8[1]); o.y = pack2(a8[2], a8[3]); o.z = pack2(a8[4], a8[5]); o.w = pack2(a8[6], a8[7]);
;     *(uint4*)((isK ? Ks : Qs) + t * 136 + chl) = o;
	v_lshlrev_b32_e32 v188, 16, v166
	v_and_b32_e32 v189, 0xffff0000, v166
	v_lshlrev_b32_e32 v190, 16, v167
	v_and_b32_e32 v191, 0xffff0000, v167
	v_lshlrev_b32_e32 v192, 16, v168
	v_and_b32_e32 v193, 0xffff0000, v168
	v_lshlrev_b32_e32 v194, 16, v169
	v_and_b32_e32 v195, 0xffff0000, v169
	v_fma_f32 v204, v94, v188, v4
	v_fma_f32 v205, v95, v189, v5
	v_fma_f32 v206, v96, v190, v6
	v_fma_f32 v207, v97, v191, v7
	v_fma_f32 v208, v98, v192, v0
	v_fma_f32 v209, v99, v193, v1
	v_fma_f32 v210, v100, v194, v2
	v_fma_f32 v211, v101, v195, v3
	v_lshlrev_b32_e32 v188, 16, v170
	v_and_b32_e32 v189, 0xffff0000, v170
	v_lshlrev_b32_e32 v190, 16, v171
	v_and_b32_e32 v191, 0xffff0000, v171
	v_lshlrev_b32_e32 v192, 16, v172
	v_and_b32_e32 v193, 0xffff0000, v172
	v_lshlrev_b32_e32 v194, 16, v173
	v_and_b32_e32 v195, 0xffff0000, v173
	v_fmac_f32_e32 v204, v102, v188
	v_fmac_f32_e32 v205, v103, v189
	v_fmac_f32_e32 v206, v104, v190
	v_fmac_f32_e32 v207, v105, v191
	v_fmac_f32_e32 v208, v106, v192
	v_fmac_f32_e32 v209, v107, v193
	v_fmac_f32_e32 v210, v108, v194
	v_fmac_f32_e32 v211, v109, v195
	v_lshlrev_b32_e32 v188, 16, v174
	v_and_b32_e32 v189, 0xffff0000, v174
	v_lshlrev_b32_e32 v190, 16, v175
	v_and_b32_e32 v191, 0xffff0000, v175
	v_lshlrev_b32_e32 v192, 16, v176
	v_and_b32_e32 v193, 0xffff0000, v176
	v_lshlrev_b32_e32 v194, 16, v177
	v_and_b32_e32 v195, 0xffff0000, v177
	v_fmac_f32_e32 v204, v110, v188
	v_fmac_f32_e32 v205, v111, v189
	v_fmac_f32_e32 v206, v112, v190
	v_fmac_f32_e32 v207, v113, v191
	v_fmac_f32_e32 v208, v114, v192
	v_fmac_f32_e32 v209, v115, v193
	v_fmac_f32_e32 v210, v116, v194
	v_fmac_f32_e32 v211, v117, v195
	v_lshlrev_b32_e32 v188, 16, v178
	v_and_b32_e32 v189, 0xffff0000, v178
	v_lshlrev_b32_e32 v190, 16, v179
	v_and_b32_e32 v191, 0xffff0000, v179
	v_lshlrev_b32_e32 v192, 16, v180
	v_and_b32_e32 v193, 0xffff0000, v180
	v_lshlrev_b32_e32 v194, 16, v181
	v_and_b32_e32 v195, 0xffff0000, v181
	v_fmac_f32_e32 v204, v8, v188
	v_fmac_f32_e32 v205, v9, v189
	v_fmac_f32_e32 v206, v10, v190
	v_fmac_f32_e32 v207, v11, v191
	v_fmac_f32_e32 v208, v12, v192
	v_fmac_f32_e32 v209, v13, v193
	v_fmac_f32_e32 v210, v14, v194
	v_fmac_f32_e32 v211, v15, v195
	v_mul_f32_e32 v212, 0xbfb8aa3b, v204
	v_mul_f32_e32 v213, 0xbfb8aa3b, v205
	v_mul_f32_e32 v214, 0xbfb8aa3b, v206
	v_mul_f32_e32 v215, 0xbfb8aa3b, v207
	v_mul_f32_e32 v216, 0xbfb8aa3b, v208
	v_mul_f32_e32 v217, 0xbfb8aa3b, v209
	v_mul_f32_e32 v218, 0xbfb8aa3b, v210
	v_mul_f32_e32 v219, 0xbfb8aa3b, v211
	v_mul_f32_e32 v188, v26, v204
	v_mul_f32_e32 v189, v27, v205
	v_mul_f32_e32 v190, v26, v206
	v_mul_f32_e32 v191, v27, v207
	v_mul_f32_e32 v192, v26, v208
	v_mul_f32_e32 v193, v27, v209
	v_mul_f32_e32 v194, v26, v210
	v_mul_f32_e32 v195, v27, v211
	v_exp_f32_e32 v212, v212
	v_exp_f32_e32 v213, v213
	v_exp_f32_e32 v214, v214
	v_exp_f32_e32 v215, v215
	v_exp_f32_e32 v216, v216
	v_exp_f32_e32 v217, v217
	v_exp_f32_e32 v218, v218
	v_exp_f32_e32 v219, v219
	v_add_f32_e32 v212, 1.0, v212
	v_add_f32_e32 v213, 1.0, v213
	v_add_f32_e32 v214, 1.0, v214
	v_add_f32_e32 v215, 1.0, v215
	v_add_f32_e32 v216, 1.0, v216
	v_add_f32_e32 v217, 1.0, v217
	v_add_f32_e32 v218, 1.0, v218
	v_add_f32_e32 v219, 1.0, v219
	v_rcp_f32_e32 v212, v212
	v_rcp_f32_e32 v213, v213
	v_rcp_f32_e32 v214, v214
	v_rcp_f32_e32 v215, v215
	v_rcp_f32_e32 v216, v216
	v_rcp_f32_e32 v217, v217
	v_rcp_f32_e32 v218, v218
	v_rcp_f32_e32 v219, v219
	v_mul_f32_e32 v188, v188, v212
	v_mul_f32_e32 v189, v189, v213
	v_mul_f32_e32 v190, v190, v214
	v_mul_f32_e32 v191, v191, v215
	v_mul_f32_e32 v192, v192, v216
	v_mul_f32_e32 v193, v193, v217
	v_mul_f32_e32 v194, v194, v218
	v_mul_f32_e32 v195, v195, v219
	v_cvt_pk_bf16_f32 v196, v188, v189
	v_cvt_pk_bf16_f32 v197, v190, v191
	v_cvt_pk_bf16_f32 v198, v192, v193
	v_cvt_pk_bf16_f32 v199, v194, v195
	ds_write_b128 v54, v[196:199] offset:15232

; DI float bf2f(u16 h) { return __uint_as_float(((unsigned)h) << 16); }
; DI void mlstmC_pair(const Params& p, char* lds_all, int pair) {
;     ...
;   {
;     const int t = ltid & 63, part = ltid >> 6;
;     float acc = 0.f;
;     if (c > 0) for (int dd = 0; dd < 32; ++dd) acc += bf2f(Qs[t * 136 + part * 32 + dd]) * NP[part * 32 + dd];
;     qnp[part * 64 + t] = acc;
;   }
.LBB0_582:
	s_or_b64 exec, exec, s[6:7]
	v_lshrrev_b32_e32 v28, 6, v42
	v_lshlrev_b32_e32 v37, 5, v28
	v_mov_b32_e32 v29, 0
	v_mov_b32_e32 v0, 0
	s_waitcnt lgkmcnt(0)
	s_barrier
	s_and_saveexec_b64 s[0:1], vcc
	s_cbranch_execz .LBB0_584
	v_lshlrev_b64 v[0:1], 9, v[24:25]
	v_lshl_add_u64 v[16:17], s[60:61], 0, v[0:1]
	v_mul_u32_u24_e32 v0, 0x110, v26
	v_lshlrev_b32_e32 v1, 1, v37
	v_lshlrev_b32_e32 v20, 2, v37
	v_add3_u32 v4, v51, v0, v1
	v_lshl_add_u64 v[34:35], v[16:17], 0, v[20:21]
	ds_read_b128 v[0:3], v4
	ds_read_b128 v[12:15], v4 offset:16
	ds_read_b128 v[8:11], v4 offset:32
	ds_read_b128 v[4:7], v4 offset:48
	global_load_dwordx4 v[16:19], v[34:35], off offset:48
	global_load_dwordx4 v[30:33], v[34:35], off offset:32
	global_load_dwordx4 v[38:41], v[34:35], off offset:16
	global_load_dwordx4 v[54:57], v[34:35], off
	s_waitcnt lgkmcnt(3)
	v_lshlrev_b32_e32 v43, 16, v0
	v_and_b32_e32 v0, 0xffff0000, v0
	s_waitcnt vmcnt(0)
	v_fma_f32 v20, v54, v43, 0
	v_fmac_f32_e32 v20, v55, v0
	v_lshlrev_b32_e32 v0, 16, v1
	v_fmac_f32_e32 v20, v56, v0
	v_and_b32_e32 v0, 0xffff0000, v1
	v_fmac_f32_e32 v20, v57, v0
	v_lshlrev_b32_e32 v0, 16, v2
	v_fmac_f32_e32 v20, v38, v0
	v_and_b32_e32 v0, 0xffff0000, v2
	v_fmac_f32_e32 v20, v39, v0
	v_lshlrev_b32_e32 v0, 16, v3
	v_fmac_f32_e32 v20, v40, v0
	v_and_b32_e32 v0, 0xffff0000, v3
	v_fmac_f32_e32 v20, v41, v0
	s_waitcnt lgkmcnt(2)
	v_lshlrev_b32_e32 v0, 16, v12
	v_fmac_f32_e32 v20, v30, v0
	v_and_b32_e32 v0, 0xffff0000, v12
	v_fmac_f32_e32 v20, v31, v0
	v_lshlrev_b32_e32 v0, 16, v13
	v_fmac_f32_e32 v20, v32, v0
	v_and_b32_e32 v0, 0xffff0000, v13
	v_fmac_f32_e32 v20, v33, v0
	v_lshlrev_b32_e32 v0, 16, v14
	v_fmac_f32_e32 v20, v16, v0
	v_and_b32_e32 v0, 0xffff0000, v14
	v_fmac_f32_e32 v20, v17, v0
	v_lshlrev_b32_e32 v0, 16, v15
	v_fmac_f32_e32 v20, v18, v0
	v_and_b32_e32 v0, 0xffff0000, v15
	v_fmac_f32_e32 v20, v19, v0
	global_load_dwordx4 v[16:19], v[34:35], off offset:64
	global_load_dwordx4 v[0:3], v[34:35], off offset:112
	global_load_dwordx4 v[12:15], v[34:35], off offset:96
	global_load_dwordx4 v[30:33], v[34:35], off offset:80
	s_waitcnt lgkmcnt(1)
	v_lshlrev_b32_e32 v38, 16, v8
	v_and_b32_e32 v8, 0xffff0000, v8
	s_waitcnt vmcnt(3)
	v_fmac_f32_e32 v20, v16, v38
	v_fmac_f32_e32 v20, v17, v8
	v_lshlrev_b32_e32 v8, 16, v9
	v_fmac_f32_e32 v20, v18, v8
	v_and_b32_e32 v8, 0xffff0000, v9
	v_fmac_f32_e32 v20, v19, v8
	v_and_b32_e32 v9, 0xffff0000, v10
	v_lshlrev_b32_e32 v8, 16, v10
	s_waitcnt vmcnt(0)
	v_mul_f32_e32 v8, v30, v8
	v_mul_f32_e32 v9, v31, v9
	s_nop 0
	v_add_f32_e32 v8, v20, v8
	v_add_f32_e32 v10, v8, v9
	v_and_b32_e32 v9, 0xffff0000, v11
	v_lshlrev_b32_e32 v8, 16, v11
	v_mul_f32_e32 v8, v32, v8
	v_mul_f32_e32 v9, v33, v9
	s_nop 0
	v_add_f32_e32 v8, v10, v8
	v_add_f32_e32 v10, v8, v9
	s_waitcnt lgkmcnt(0)
	v_and_b32_e32 v9, 0xffff0000, v4
	v_lshlrev_b32_e32 v8, 16, v4
	v_mul_f32_e32 v8, v12, v8
	v_mul_f32_e32 v9, v13, v9
	s_nop 0
	v_add_f32_e32 v4, v10, v8
	v_add_f32_e32 v10, v4, v9
	v_and_b32_e32 v9, 0xffff0000, v5
	v_lshlrev_b32_e32 v8, 16, v5
	v_mul_f32_e32 v4, v14, v8
	v_mul_f32_e32 v5, v15, v9
	s_nop 0
	v_add_f32_e32 v4, v10, v4
	v_add_f32_e32 v8, v4, v5
	v_and_b32_e32 v5, 0xffff0000, v6
	v_lshlrev_b32_e32 v4, 16, v6
	v_mul_f32_e32 v0, v0, v4
	v_mul_f32_e32 v1, v1, v5
	s_nop 0
	v_add_f32_e32 v0, v8, v0
	v_add_f32_e32 v4, v0, v1
	v_and_b32_e32 v1, 0xffff0000, v7
	v_lshlrev_b32_e32 v0, 16, v7
	v_mul_f32_e32 v0, v2, v0
	v_mul_f32_e32 v1, v3, v1
	s_nop 0
	v_add_f32_e32 v0, v4, v0
	v_add_f32_e32 v0, v0, v1

; #define MFMA(a, b, c) __builtin_amdgcn_mfma_f32_32x32x16_bf16((a), (b), (c), 0, 0, 0)
; DI f32x16 zero16() { f32x16 z; for (int i = 0; i < 16; ++i) z[i] = 0.f; return z; }
; DI void mlstmC_pair(const Params& p, char* lds_all, int pair) {
;     ...
;   for (int tt = 0; tt < 2; ++tt) {
;     const int tq = tt * 32 + l31;
;     Hn[tt] = zero16();
;     if (c > 0) {
; #pragma unroll
;       for (int kk = 0; kk < 8; ++kk) Hn[tt] = MFMA(ldfrag(CT + (et * 32 + l31) * 128 + kk * 16 + 8 * hh), ldfrag(Qs + tq * 136 + kk * 16 + 8 * hh), Hn[tt]);
;     }
;     const float wi = wint[tq];
; #pragma unroll
;     for (int r = 0; r < 16; ++r) Hn[tt][r] *= wi;
; #pragma unroll
;     for (int ks = 0; ks < 4; ++ks) Hn[tt] = MFMA(ldfrag(VTs + (et * 32 + l31) * 72 + ks * 16 + 8 * hh), ldfrag(Ps + tq * 72 + ks * 16 + 8 * hh), Hn[tt]);
;     const float qn = qnp[tq] + qnp[64 + tq] + qnp[128 + tq] + qnp[192 + tq];
;     const float den = wi * qn + qks[tq] + qks[64 + tq];
;     const float inv = __builtin_amdgcn_rcpf(fmaxf(fabsf(den), emt[tq]));
;     float s1 = 0.f, s2 = 0.f;
; #pragma unroll
;     for (int r = 0; r < 16; ++r) { Hn[tt][r] *= inv; s1 += Hn[tt][r]; s2 += Hn[tt][r] * Hn[tt][r]; }
;     s1 += __shfl_xor(s1, 32); s2 += __shfl_xor(s2, 32);
;     if (hh == 0) { red[(et * 64 + tq) * 2] = s1; red[(et * 64 + tq) * 2 + 1] = s2; }
.LBB0_620:
	s_or_b64 exec, exec, s[4:5]
	v_or_b32_e32 v19, v37, v53
	v_mul_u32_u24_e32 v19, 0x90, v19
	v_add3_u32 v18, v51, v19, v18
	v_lshl_add_u32 v19, v53, 2, v51
	ds_read2st64_b32 v[34:35], v19 offset0:246 offset1:247
	s_movk_i32 s2, 0x90
	v_mad_u32_u24 v20, v53, s2, v29
	ds_read_b128 v[24:27], v18 offset:34816
	ds_read_b128 v[30:33], v18 offset:34848
	ds_read_b128 v[38:41], v20 offset:53248
	ds_read_b128 v[42:45], v20 offset:53280
	s_waitcnt lgkmcnt(4)
	v_mul_f32_e32 v14, v34, v14
	v_mul_f32_e32 v15, v34, v15
	v_mul_f32_e32 v12, v34, v12
	v_mul_f32_e32 v13, v34, v13
	v_mul_f32_e32 v10, v34, v10
	v_mul_f32_e32 v11, v34, v11
	v_mul_f32_e32 v8, v34, v8
	v_mul_f32_e32 v9, v34, v9
	v_mul_f32_e32 v6, v34, v6
	v_mul_f32_e32 v7, v34, v7
	v_mul_f32_e32 v4, v34, v4
	v_mul_f32_e32 v5, v34, v5
	v_mul_f32_e32 v2, v34, v2
	v_mul_f32_e32 v3, v34, v3
	v_mul_f32_e32 v0, v34, v0
	v_mul_f32_e32 v1, v34, v1
	s_waitcnt lgkmcnt(1)
	s_nop 0
	v_mfma_f32_32x32x16_bf16 v[0:15], v[24:27], v[38:41], v[0:15]
	s_waitcnt lgkmcnt(0)
	v_mfma_f32_32x32x16_bf16 v[0:15], v[30:33], v[42:45], v[0:15]
	ds_read_b128 v[24:27], v18 offset:34880
	ds_read_b128 v[30:33], v20 offset:53312
	s_waitcnt lgkmcnt(0)
	v_mfma_f32_32x32x16_bf16 v[0:15], v[24:27], v[30:33], v[0:15]
	ds_read_b128 v[24:27], v18 offset:34912
	ds_read_b128 v[30:33], v20 offset:53344
	s_waitcnt lgkmcnt(0)
	v_mfma_f32_32x32x16_bf16 v[0:15], v[24:27], v[30:33], v[0:15]
	ds_read2st64_b32 v[24:25], v19 offset0:248 offset1:249
	s_waitcnt lgkmcnt(0)
	v_add_f32_e32 v20, v24, v25
	ds_read2st64_b32 v[24:25], v19 offset0:250 offset1:251
	s_waitcnt lgkmcnt(0)
	v_add_f32_e32 v20, v20, v24
	v_add_f32_e32 v20, v20, v25
	ds_read2st64_b32 v[24:25], v19 offset0:252 offset1:253
	s_waitcnt lgkmcnt(0)
	v_fma_f32 v20, v34, v20, v24
	v_add_f32_e32 v20, v25, v20
	v_max_f32_e32 v24, v35, v35
	v_max_f32_e64 v20, |v20|, v24
	v_rcp_f32_e32 v20, v20
	s_nop 0
	v_mul_f32_e32 v42, v0, v20
	v_mul_f32_e32 v43, v1, v20
	s_nop 0
	v_add_f32_e32 v0, 0, v42
	v_add_f32_e32 v24, v43, v0
	v_mul_f32_e32 v44, v2, v20
	v_mul_f32_e32 v45, v3, v20
	v_mul_f32_e32 v0, v43, v43
	v_add_f32_e32 v2, v44, v24
	v_fma_f32 v1, v43, v43, v0
	v_fmac_f32_e32 v0, v42, v42
	v_add_f32_e32 v2, v45, v2
	v_mul_f32_e32 v38, v4, v20
	v_mul_f32_e32 v39, v5, v20
	v_fmac_f32_e32 v0, v44, v44
	v_fmac_f32_e32 v1, v45, v45
	v_add_f32_e32 v5, v38, v2
	v_mul_f32_e32 v4, v45, v45
	v_mov_b32_e32 v2, v38
	v_mov_b32_e32 v3, v45
	v_add_f32_e32 v0, v4, v0
	v_add_f32_e32 v1, v4, v1
	v_fmac_f32_e32 v0, v2, v2
	v_fmac_f32_e32 v1, v3, v3
	v_add_f32_e32 v2, v39, v5
	v_mul_f32_e32 v40, v6, v20
	v_mul_f32_e32 v41, v7, v20
	v_mul_f32_e32 v4, v39, v39
	v_add_f32_e32 v5, v40, v2
	v_mov_b32_e32 v2, v40
	v_mov_b32_e32 v3, v39
	v_add_f32_e32 v0, v4, v0
	v_add_f32_e32 v1, v4, v1
	v_fmac_f32_e32 v0, v2, v2
	v_fmac_f32_e32 v1, v3, v3
	v_add_f32_e32 v2, v41, v5
	v_mul_f32_e32 v32, v8, v20
	v_mul_f32_e32 v33, v9, v20
	v_mul_f32_e32 v4, v41, v41
	v_add_f32_e32 v5, v32, v2
	v_mov_b32_e32 v2, v32
	v_mov_b32_e32 v3, v41
	v_add_f32_e32 v0, v4, v0
	v_add_f32_e32 v1, v4, v1
	v_fmac_f32_e32 v0, v2, v2
	v_fmac_f32_e32 v1, v3, v3
	v_add_f32_e32 v2, v33, v5
	v_mul_f32_e32 v34, v10, v20
	v_mul_f32_e32 v35, v11, v20
	v_mul_f32_e32 v4, v33, v33
	v_add_f32_e32 v5, v34, v2
	v_mov_b32_e32 v2, v34
	v_mov_b32_e32 v3, v33
	v_add_f32_e32 v0, v4, v0
	v_add_f32_e32 v1, v4, v1
	v_fmac_f32_e32 v0, v2, v2
	v_fmac_f32_e32 v1, v3, v3
	v_add_f32_e32 v2, v35, v5
	v_mul_f32_e32 v24, v12, v20
	v_mul_f32_e32 v25, v13, v20
	v_mul_f32_e32 v4, v35, v35
	v_add_f32_e32 v5, v24, v2
	v_mov_b32_e32 v2, v24
	v_mov_b32_e32 v3, v35
	v_add_f32_e32 v0, v4, v0
	v_add_f32_e32 v1, v4, v1
	v_fmac_f32_e32 v0, v2, v2
	v_fmac_f32_e32 v1, v3, v3
	v_mul_f32_e32 v26, v14, v20
	v_mul_f32_e32 v27, v15, v20
	v_mul_f32_e32 v6, v25, v25
	v_add_f32_e32 v2, v25, v5
	v_mov_b32_e32 v4, v26
	v_mov_b32_e32 v5, v25
	v_add_f32_e32 v0, v6, v0
	v_add_f32_e32 v1, v6, v1
	v_fmac_f32_e32 v0, v4, v4
	v_fmac_f32_e32 v1, v5, v5
	v_mul_f32_e32 v4, v26, v26
	v_mul_f32_e32 v5, v27, v27
	v_add_f32_e32 v2, v26, v2
	v_pk_mov_b32 v[0:1], v[26:27], v[0:1] op_sel:[1,0]
	v_mov_b32_e32 v3, v5
	v_add_f32_e32 v0, v0, v2
	v_add_f32_e32 v1, v1, v3
	ds_bpermute_b32 v2, v55, v0
	ds_bpermute_b32 v3, v55, v1
	s_and_saveexec_b64 s[4:5], s[0:1]
	s_cbranch_execz .LBB0_622
	v_and_b32_e32 v4, 0x6f8, v52
	v_add_u32_e32 v4, v51, v4
	s_waitcnt lgkmcnt(0)
	v_add_f32_e32 v0, v0, v2
	v_add_f32_e32 v1, v1, v3
	ds_write_b64 v4, v[0:1] offset:65024

; #define MFMA(a, b, c) __builtin_amdgcn_mfma_f32_32x32x16_bf16((a), (b), (c), 0, 0, 0)
; DI f32x16 zero16() { f32x16 z; for (int i = 0; i < 16; ++i) z[i] = 0.f; return z; }
; DI void mlstmC_pair(const Params& p, char* lds_all, int pair) {
;     ...
;   for (int tt = 0; tt < 2; ++tt) {
;     const int tq = tt * 32 + l31;
;     Hn[tt] = zero16();
;     if (c > 0) {
; #pragma unroll
;       for (int kk = 0; kk < 8; ++kk) Hn[tt] = MFMA(ldfrag(CT + (et * 32 + l31) * 128 + kk * 16 + 8 * hh), ldfrag(Qs + tq * 136 + kk * 16 + 8 * hh), Hn[tt]);
;     }
;     const float wi = wint[tq];
; #pragma unroll
;     for (int r = 0; r < 16; ++r) Hn[tt][r] *= wi;
; #pragma unroll
;     for (int ks = 0; ks < 4; ++ks) Hn[tt] = MFMA(ldfrag(VTs + (et * 32 + l31) * 72 + ks * 16 + 8 * hh), ldfrag(Ps + tq * 72 + ks * 16 + 8 * hh), Hn[tt]);
;     const float qn = qnp[tq] + qnp[64 + tq] + qnp[128 + tq] + qnp[192 + tq];
;     const float den = wi * qn + qks[tq] + qks[64 + tq];
;     const float inv = __builtin_amdgcn_rcpf(fmaxf(fabsf(den), emt[tq]));
;     float s1 = 0.f, s2 = 0.f;
; #pragma unroll
;     for (int r = 0; r < 16; ++r) { Hn[tt][r] *= inv; s1 += Hn[tt][r]; s2 += Hn[tt][r] * Hn[tt][r]; }
;     s1 += __shfl_xor(s1, 32); s2 += __shfl_xor(s2, 32);
;     if (hh == 0) { red[(et * 64 + tq) * 2] = s1; red[(et * 64 + tq) * 2 + 1] = s2; }
;   }
.LBB0_624:
	s_or_b64 exec, exec, s[4:5]
	v_add_u32_e32 v20, 0x80, v19
	ds_read2st64_b32 v[68:69], v20 offset0:246 offset1:247
	v_mul_u32_u24_e32 v16, 0x90, v53
	v_add_u32_e32 v70, v16, v29
	ds_read_b128 v[28:31], v18 offset:34816
	ds_read_b128 v[56:59], v18 offset:34848
	ds_read_b128 v[60:63], v70 offset:57856
	ds_read_b128 v[64:67], v70 offset:57888
	s_waitcnt lgkmcnt(4)
	s_nop 1
	v_mul_f32_e32 v14, v68, v14
	v_mul_f32_e32 v15, v68, v15
	v_mul_f32_e32 v12, v68, v12
	v_mul_f32_e32 v13, v68, v13
	v_mul_f32_e32 v10, v68, v10
	v_mul_f32_e32 v11, v68, v11
	v_mul_f32_e32 v8, v68, v8
	v_mul_f32_e32 v9, v68, v9
	v_mul_f32_e32 v6, v68, v6
	v_mul_f32_e32 v7, v68, v7
	v_mul_f32_e32 v4, v68, v4
	v_mul_f32_e32 v5, v68, v5
	v_mul_f32_e32 v2, v68, v2
	v_mul_f32_e32 v3, v68, v3
	v_mul_f32_e32 v0, v68, v0
	v_mul_f32_e32 v1, v68, v1
	s_waitcnt lgkmcnt(1)
	s_nop 0
	v_mfma_f32_32x32x16_bf16 v[0:15], v[28:31], v[60:63], v[0:15]
	s_waitcnt lgkmcnt(0)
	v_mfma_f32_32x32x16_bf16 v[0:15], v[56:59], v[64:67], v[0:15]
	ds_read_b128 v[28:31], v18 offset:34880
	ds_read_b128 v[56:59], v70 offset:57920
	s_waitcnt lgkmcnt(0)
	v_mfma_f32_32x32x16_bf16 v[0:15], v[28:31], v[56:59], v[0:15]
	ds_read_b128 v[16:19], v18 offset:34912
	ds_read_b128 v[28:31], v70 offset:57952
	s_waitcnt lgkmcnt(0)
	v_mfma_f32_32x32x16_bf16 v[0:15], v[16:19], v[28:31], v[0:15]
	ds_read2st64_b32 v[16:17], v20 offset0:248 offset1:249
	s_waitcnt lgkmcnt(0)
	v_add_f32_e32 v18, v16, v17
	ds_read2st64_b32 v[16:17], v20 offset0:250 offset1:251
	s_waitcnt lgkmcnt(0)
	v_add_f32_e32 v16, v18, v16
	v_add_f32_e32 v18, v16, v17
	ds_read2st64_b32 v[16:17], v20 offset0:252 offset1:253
	s_waitcnt lgkmcnt(0)
	v_fma_f32 v16, v68, v18, v16
	v_add_f32_e32 v16, v17, v16
	v_max_f32_e32 v17, v69, v69
	v_max_f32_e64 v16, |v16|, v17
	v_rcp_f32_e32 v20, v16
	s_nop 0
	v_mul_f32_e32 v28, v0, v20
	v_mul_f32_e32 v29, v1, v20
	s_nop 0
	v_add_f32_e32 v0, 0, v28
	v_add_f32_e32 v16, v29, v0
	v_mul_f32_e32 v30, v2, v20
	v_mul_f32_e32 v31, v3, v20
	v_mul_f32_e32 v0, v29, v29
	v_add_f32_e32 v2, v30, v16
	v_fma_f32 v1, v29, v29, v0
	v_fmac_f32_e32 v0, v28, v28
	v_add_f32_e32 v2, v31, v2
	v_mul_f32_e32 v16, v4, v20
	v_mul_f32_e32 v17, v5, v20
	v_fmac_f32_e32 v0, v30, v30
	v_fmac_f32_e32 v1, v31, v31
	v_add_f32_e32 v5, v16, v2
	v_mul_f32_e32 v4, v31, v31
	v_mov_b32_e32 v2, v16
	v_mov_b32_e32 v3, v31
	v_add_f32_e32 v0, v4, v0
	v_add_f32_e32 v1, v4, v1
	v_fmac_f32_e32 v0, v2, v2
	v_fmac_f32_e32 v1, v3, v3
	v_add_f32_e32 v2, v17, v5
	v_mul_f32_e32 v18, v6, v20
	v_mul_f32_e32 v19, v7, v20
	v_mul_f32_e32 v4, v17, v17
	v_add_f32_e32 v5, v18, v2
	v_mov_b32_e32 v2, v18
	v_mov_b32_e32 v3, v17
	v_add_f32_e32 v0, v4, v0
	v_add_f32_e32 v1, v4, v1
	v_fmac_f32_e32 v0, v2, v2
	v_fmac_f32_e32 v1, v3, v3
	v_add_f32_e32 v2, v19, v5
	v_mul_f32_e32 v6, v8, v20
	v_mul_f32_e32 v7, v9, v20
	v_mul_f32_e32 v4, v19, v19
	v_add_f32_e32 v5, v6, v2
	v_mov_b32_e32 v2, v6
	v_mov_b32_e32 v3, v19
	v_add_f32_e32 v0, v4, v0
	v_add_f32_e32 v1, v4, v1
	v_fmac_f32_e32 v0, v2, v2
	v_fmac_f32_e32 v1, v3, v3
	v_add_f32_e32 v2, v7, v5
	v_mul_f32_e32 v8, v10, v20
	v_mul_f32_e32 v9, v11, v20
	v_mul_f32_e32 v4, v7, v7
	v_add_f32_e32 v5, v8, v2
	v_mov_b32_e32 v2, v8
	v_mov_b32_e32 v3, v7
	v_add_f32_e32 v0, v4, v0
	v_add_f32_e32 v1, v4, v1
	v_fma_f32 v2, v2, v2, v0
	v_fma_f32 v3, v3, v3, v1
	v_add_f32_e32 v4, v9, v5
	v_mul_f32_e32 v0, v12, v20
	v_mul_f32_e32 v1, v13, v20
	v_mul_f32_e32 v10, v9, v9
	v_add_f32_e32 v11, v0, v4
	v_mov_b32_e32 v4, v0
	v_mov_b32_e32 v5, v9
	v_add_f32_e32 v2, v10, v2
	v_add_f32_e32 v3, v10, v3
	v_fma_f32 v4, v4, v4, v2
	v_fma_f32 v5, v5, v5, v3
	v_mul_f32_e32 v2, v14, v20
	v_mul_f32_e32 v3, v15, v20
	v_mul_f32_e32 v14, v1, v1
	v_mov_b32_e32 v12, v2
	v_mov_b32_e32 v13, v1
	v_add_f32_e32 v4, v14, v4
	v_add_f32_e32 v5, v14, v5
	v_add_f32_e32 v10, v1, v11
	v_fmac_f32_e32 v4, v12, v12
	v_fmac_f32_e32 v5, v13, v13
	v_mul_f32_e32 v12, v2, v2
	v_mul_f32_e32 v13, v3, v3
	v_add_f32_e32 v10, v2, v10
	v_pk_mov_b32 v[4:5], v[2:3], v[4:5] op_sel:[1,0]
	v_mov_b32_e32 v11, v13
	v_add_f32_e32 v4, v4, v10
	v_add_f32_e32 v5, v5, v11
	ds_bpermute_b32 v10, v55, v4
	ds_bpermute_b32 v11, v55, v5
	s_and_saveexec_b64 s[4:5], s[0:1]
	s_cbranch_execz .LBB0_569
	s_movk_i32 s0, 0xc0
	v_and_or_b32 v12, v46, s0, v52
	v_lshl_add_u32 v12, v12, 3, v51
	s_waitcnt lgkmcnt(0)
	v_add_f32_e32 v4, v4, v10
	v_add_f32_e32 v5, v5, v11
	ds_write_b64 v12, v[4:5] offset:65024
	s_branch .LBB0_569
